# GLU phase: every unit computed by two workgroups (same GEMM), each finishing one 128-row half of the epilogue; weight transposes on the remaining 64 idle workgroups
# speedup vs baseline: 1.0020x; 1.0020x over previous
.Lp6_tr:
	s_mov_b64 s[16:17], s[0:1]
	s_load_dwordx2 s[18:19], s[0:1], 0xe8
	s_sub_i32 s28, s2, 0xc0
	s_movk_i32 s45, 0x40
	s_waitcnt lgkmcnt(0)
	s_add_u32 s20, s18, 0x7bc000
	s_addc_u32 s21, s19, 0
	v_mov_b32_e32 v0, v170
	s_cmpk_gt_i32 s28, 0x1ff
	s_cbranch_scc1 .Lp6_ret
	v_add_u32_e32 v3, 0x200, v0
	v_ashrrev_i32_e32 v5, 6, v3
	v_add_u32_e32 v3, 0x400, v0
	v_ashrrev_i32_e32 v6, 6, v3
	v_add_u32_e32 v3, 0x600, v0
	v_ashrrev_i32_e32 v7, 6, v3
	v_add_u32_e32 v3, 0x800, v0
	v_ashrrev_i32_e32 v8, 6, v3
	v_add_u32_e32 v3, 0xa00, v0
	s_add_u32 s4, s18, 0x1ebc000
	v_ashrrev_i32_e32 v9, 6, v3
	v_add_u32_e32 v3, 0xc00, v0
	s_addc_u32 s5, s19, 0
	v_ashrrev_i32_e32 v10, 6, v3
	v_add_u32_e32 v3, 0xe00, v0
	s_add_u32 s29, s18, 0xebc000
	v_ashrrev_i32_e32 v11, 6, v3
	v_bfe_u32 v3, v0, 4, 2
	v_lshlrev_b32_e32 v12, 4, v0
	s_addc_u32 s30, s19, 0
	v_mul_u32_u24_e32 v3, 0x4100, v3
	v_and_b32_e32 v12, 0xf0, v12
	s_add_u32 s31, s18, 0xe3c000
	v_lshlrev_b32_e32 v1, 2, v0
	v_ashrrev_i32_e32 v4, 6, v0
	v_add3_u32 v3, 0, v3, v12
	v_ashrrev_i32_e32 v12, 3, v0
	v_lshlrev_b32_e32 v0, 3, v0
	s_addc_u32 s35, s19, 0
	v_and_b32_e32 v24, 56, v0
	s_add_u32 s6, s18, 0xdbc000
	v_mul_u32_u24_e32 v0, 0x41, v24
	s_addc_u32 s7, s19, 0
	s_movk_i32 s10, 0x104
	v_lshlrev_b32_e32 v14, 2, v12
	v_lshlrev_b32_e32 v0, 2, v0
	s_add_u32 s8, s18, 0xbbc000
	v_and_b32_e32 v2, 0xfc, v1
	v_mov_b32_e32 v1, 0
	v_mul_lo_u32 v15, v4, s10
	v_mul_lo_u32 v16, v5, s10
	v_mul_lo_u32 v17, v6, s10
	v_mul_lo_u32 v18, v7, s10
	v_mul_lo_u32 v19, v8, s10
	v_mul_lo_u32 v20, v9, s10
	v_mul_lo_u32 v21, v10, s10
	v_mul_lo_u32 v22, v11, s10
	v_add3_u32 v13, 0, v14, v0
	v_add3_u32 v14, 0, v0, v14
	s_addc_u32 s9, s19, 0
	s_mov_b32 s11, 0
	s_movk_i32 s36, 0xe0
	v_lshlrev_b32_e32 v0, 2, v2
	v_add_u32_e32 v15, v3, v15
	v_add_u32_e32 v16, v3, v16
	v_add_u32_e32 v17, v3, v17
	v_add_u32_e32 v18, v3, v18
	v_add_u32_e32 v19, v3, v19
	v_add_u32_e32 v20, v3, v20
	v_add_u32_e32 v21, v3, v21
	v_add_u32_e32 v22, v3, v22
	v_lshlrev_b32_e32 v2, 1, v24
	v_mov_b32_e32 v3, v1
	v_add_u32_e32 v23, 0x400, v13
	v_add_u32_e32 v24, 0x400, v14
	v_add_u32_e32 v25, 0x4000, v13
	v_add_u32_e32 v26, 0x4200, v14
	v_add_u32_e32 v27, 0x4400, v13
	v_add_u32_e32 v28, 0x4600, v14
	v_add_u32_e32 v29, 0x8200, v13
	v_add_u32_e32 v30, 0x8200, v14
	v_add_u32_e32 v31, 0x8600, v13
	v_add_u32_e32 v32, 0x8600, v14
	v_add_u32_e32 v33, 0xc200, v13
	v_add_u32_e32 v34, 0xc400, v14
	v_add_u32_e32 v35, 0xc600, v13
	v_add_u32_e32 v36, 0xc800, v14
	s_mov_b32 s37, s28
	s_branch .LBB0_804

.Lxbn4_end:
.LBB0_1170:
	s_or_b64 exec, exec, s[4:5]
	s_mov_b64 s[4:5], s[0:1]
	v_mov_b32_e32 v8, v170
	s_waitcnt lgkmcnt(0)
	s_barrier
	s_cmpk_gt_i32 s2, 0xbf
	v_readfirstlane_b32 s30, v8
	s_cbranch_scc1 .Lp6_tr
	v_lshlrev_b32_e32 v0, 4, v8
	v_add_u32_e32 v1, 0x2000, v0
	v_ashrrev_i32_e32 v2, 31, v1
	v_lshrrev_b32_e32 v2, 22, v2
	v_add_u32_e32 v2, v1, v2
	v_ashrrev_i32_e32 v9, 10, v2
	v_mul_i32_i24_e32 v3, 0x400, v9
	v_sub_u32_e32 v1, v1, v3
	v_lshrrev_b32_e32 v3, 4, v1
	s_load_dwordx2 s[12:13], s[4:5], 0xe8
	v_bitop3_b32 v1, v3, v1, 32 bitop3:0x6c
	v_ashrrev_i32_e32 v3, 31, v1
	v_lshrrev_b32_e32 v3, 26, v3
	v_add_u32_e32 v3, v1, v3
	v_ashrrev_i32_e32 v10, 6, v3
	v_and_b32_e32 v3, 0xc0, v3
	s_waitcnt lgkmcnt(0)
	s_add_u32 s31, s12, 0xdbc000
	v_sub_u32_e32 v1, v1, v3
	v_mov_b32_e32 v3, 1
	s_addc_u32 s34, s13, 0
	v_lshlrev_b32_e32 v2, 5, v9
	v_ashrrev_i16_sdwa v1, v3, sext(v1) dst_sel:DWORD dst_unused:UNUSED_PAD src0_sel:DWORD src1_sel:BYTE_0
	s_add_u32 s14, s12, 0xbd9c000
	v_and_b32_e32 v2, 32, v2
	v_bfe_i32 v11, v1, 0, 16
	s_addc_u32 s15, s13, 0
	v_add_u32_e32 v1, v2, v11
	v_lshlrev_b32_e32 v2, 3, v9
	s_cmpk_gt_i32 s2, 0x5f
	s_cselect_b32 s7, 0x60, 0
	s_sub_i32 s7, s2, s7
	s_lshr_b32 s4, s3, 29
	v_and_b32_e32 v2, 0x3ffff0, v2
	s_add_i32 s4, s7, s4
	v_add_lshl_u32 v2, v10, v2, 10
	s_ashr_i32 s6, s4, 3
	s_and_b32 s4, s4, -8
	v_lshl_add_u32 v128, v1, 1, v2
	v_bfe_i32 v2, v8, 27, 1
	s_sub_i32 s4, s7, s4
	v_lshrrev_b32_e32 v2, 22, v2
	s_lshr_b32 s7, s4, 31
	v_add_u32_e32 v2, v0, v2
	s_or_b32 s7, s7, 12
	v_and_b32_e32 v2, 0xfffffc00, v2
	s_mul_i32 s4, s7, s4
	v_sub_u32_e32 v0, v0, v2
	s_add_i32 s4, s4, s6
	v_lshrrev_b32_e32 v2, 4, v0
	s_ashr_i32 s6, s4, 31
	v_bitop3_b32 v2, v2, v0, 32 bitop3:0x6c
	v_ashrrev_i32_e32 v0, 31, v0
	s_lshr_b32 s6, s6, 28
	v_lshrrev_b32_e32 v0, 26, v0
	s_add_i32 s6, s4, s6
	v_ashrrev_i32_e32 v1, 31, v8
	v_add_u32_e32 v0, v2, v0
	s_ashr_i32 s6, s6, 4
	v_lshrrev_b32_e32 v1, 26, v1
	v_ashrrev_i32_e32 v13, 6, v0
	s_lshl_b32 s8, s6, 3
	v_add_u32_e32 v1, v8, v1
	v_mul_i32_i24_e32 v0, 64, v13
	s_sub_i32 s7, 48, s8
	s_lshl_b32 s6, s6, 4
	v_ashrrev_i32_e32 v12, 6, v1
	v_sub_u32_e32 v0, v2, v0
	s_min_u32 s9, s7, 8
	s_sub_i32 s10, s4, s6
	v_lshlrev_b32_e32 v1, 5, v12
	v_ashrrev_i16_sdwa v0, v3, sext(v0) dst_sel:DWORD dst_unused:UNUSED_PAD src0_sel:DWORD src1_sel:BYTE_0
	s_sext_i32_i8 s4, s10
	v_cvt_f32_ubyte0_e32 v3, s9
	v_and_b32_e32 v1, 32, v1
	v_bfe_i32 v14, v0, 0, 16
	v_cvt_f32_i32_e32 v2, s4
	v_rcp_iflag_f32_e32 v4, v3
	v_add_u32_e32 v0, v1, v14
	v_lshlrev_b32_e32 v1, 3, v12
	v_and_b32_e32 v1, 0x3ffff0, v1
	v_add_lshl_u32 v1, v13, v1, 10
	v_lshl_add_u32 v130, v0, 1, v1
	v_mul_f32_e32 v0, v2, v4
	v_trunc_f32_e32 v0, v0
	v_fma_f32 v1, -v0, v3, v2
	v_cvt_i32_f32_e32 v0, v0
	s_ashr_i32 s16, s30, 6
	s_ashr_i32 s4, s4, 30
	s_ashr_i32 s5, s30, 8
	s_lshl_b32 s35, s16, 10
	s_or_b32 s4, s4, 1
	v_cmp_ge_f32_e64 s[6:7], |v1|, v3
	s_and_b64 s[6:7], s[6:7], exec
	s_cselect_b32 s4, s4, 0
	v_readfirstlane_b32 s6, v0
	s_add_i32 s4, s6, s4
	s_mul_i32 s6, s4, s9
	s_sub_i32 s6, s10, s6
	s_sext_i32_i8 s6, s6
	s_add_i32 s6, s8, s6
	s_ashr_i32 s7, s6, 31
	s_bfe_i64 s[8:9], s[4:5], 0x80000
	s_lshl_b64 s[10:11], s[6:7], 18
	s_lshl_b64 s[8:9], s[8:9], 18
	s_add_u32 s8, s31, s8
	s_addc_u32 s9, s34, s9
	s_add_i32 s36, s35, 0
	s_add_i32 m0, s36, 0x10000
	v_mov_b32_e32 v131, 0
	global_load_lds_dwordx4 v130, s[8:9]
	s_add_i32 m0, s36, 0x12000
	s_add_u32 s10, s14, s10
	global_load_lds_dwordx4 v128, s[8:9]
	s_addc_u32 s11, s15, s11
	s_mov_b32 m0, s36
	s_add_i32 s37, s36, 0x2000
	global_load_lds_dwordx4 v130, s[10:11]
	s_mov_b32 m0, s37
	s_add_u32 s18, s8, 0x20000
	global_load_lds_dwordx4 v128, s[10:11]
	s_addc_u32 s19, s9, 0
	s_add_i32 m0, s36, 0x14000
	v_mov_b32_e32 v129, v131
	global_load_lds_dwordx4 v130, s[18:19]
	s_add_i32 m0, s36, 0x16000
	s_mov_b32 s45, 0
	global_load_lds_dwordx4 v128, s[18:19]
	s_add_u32 s18, s10, 0x20000
	s_addc_u32 s19, s11, 0
	s_add_i32 s40, s36, 0x4000
	s_mov_b32 m0, s40
	s_add_i32 s41, s36, 0x6000
	global_load_lds_dwordx4 v130, s[18:19]
	s_mov_b32 m0, s41
	v_lshl_add_u64 v[6:7], s[8:9], 0, v[130:131]
	global_load_lds_dwordx4 v128, s[18:19]
	v_lshl_add_u64 v[4:5], s[8:9], 0, v[128:129]
	v_lshl_add_u64 v[2:3], s[10:11], 0, v[130:131]
	s_cmp_lg_u32 s5, 1
	v_lshl_add_u64 v[0:1], s[10:11], 0, v[128:129]
	s_cbranch_scc1 .LBB0_1173
	s_barrier

.LBB0_1177:
	ds_read_b128 v[140:143], v163
	ds_read_b128 v[144:147], v163 offset:1024
	ds_read_b128 v[148:151], v163 offset:2048
	ds_read_b128 v[152:155], v163 offset:3072
	s_add_u32 s10, s8, 0xfffe0080
	s_addc_u32 s11, s9, -1
	s_cmp_eq_u32 s61, 4
	s_cselect_b32 s29, s23, s11
	s_cselect_b32 s28, s57, s10
	s_cselect_b32 s11, s21, s60
	s_cselect_b32 s10, s58, s59
	v_lshl_add_u64 v[202:203], s[8:9], 0, v[134:135]
	s_add_i32 m0, s36, 0xc000
	ds_read_b128 v[156:159], v164
	ds_read_b128 v[166:169], v164 offset:1024
	ds_read_b128 v[178:181], v164 offset:2048
	ds_read_b128 v[182:185], v164 offset:3072
	ds_read_b128 v[186:189], v164 offset:4096
	ds_read_b128 v[190:193], v164 offset:5120
	ds_read_b128 v[194:197], v164 offset:6144
	ds_read_b128 v[198:201], v164 offset:7168
	global_load_lds_dwordx4 v[202:203], off
	v_lshl_add_u64 v[202:203], s[8:9], 0, v[132:133]
	s_add_i32 m0, s36, 0xe000
	s_nop 0
	global_load_lds_dwordx4 v[202:203], off
	s_waitcnt lgkmcnt(8)
	s_barrier
	s_waitcnt lgkmcnt(0)
	s_setprio 1
	s_waitcnt lgkmcnt(0)
	v_mfma_f32_16x16x32_bf16 v[124:127], v[140:143], v[156:159], v[124:127]
	v_mfma_f32_16x16x32_bf16 v[120:123], v[148:151], v[156:159], v[120:123]
	v_mfma_f32_16x16x32_bf16 v[116:119], v[140:143], v[178:181], v[116:119]
	v_mfma_f32_16x16x32_bf16 v[112:115], v[148:151], v[178:181], v[112:115]
	v_mfma_f32_16x16x32_bf16 v[108:111], v[140:143], v[186:189], v[108:111]
	v_mfma_f32_16x16x32_bf16 v[104:107], v[148:151], v[186:189], v[104:107]
	v_mfma_f32_16x16x32_bf16 v[100:103], v[140:143], v[194:197], v[100:103]
	v_mfma_f32_16x16x32_bf16 v[96:99], v[148:151], v[194:197], v[96:99]
	v_mfma_f32_16x16x32_bf16 v[124:127], v[144:147], v[166:169], v[124:127]
	v_mfma_f32_16x16x32_bf16 v[120:123], v[152:155], v[166:169], v[120:123]
	v_mfma_f32_16x16x32_bf16 v[116:119], v[144:147], v[182:185], v[116:119]
	v_mfma_f32_16x16x32_bf16 v[112:115], v[152:155], v[182:185], v[112:115]
	v_mfma_f32_16x16x32_bf16 v[108:111], v[144:147], v[190:193], v[108:111]
	v_mfma_f32_16x16x32_bf16 v[104:107], v[152:155], v[190:193], v[104:107]
	v_mfma_f32_16x16x32_bf16 v[100:103], v[144:147], v[198:201], v[100:103]
	v_mfma_f32_16x16x32_bf16 v[96:99], v[152:155], v[198:201], v[96:99]
	s_setprio 0
	s_barrier
	s_add_i32 s33, s55, s35
	v_lshl_add_u64 v[218:219], s[10:11], 0, v[130:131]
	s_mov_b32 m0, s33
	ds_read_b128 v[202:205], v165
	ds_read_b128 v[206:209], v165 offset:1024
	ds_read_b128 v[210:213], v165 offset:2048
	ds_read_b128 v[214:217], v165 offset:3072
	global_load_lds_dwordx4 v[218:219], off
	v_lshl_add_u64 v[220:221], s[10:11], 0, v[128:129]
	s_add_i32 m0, s33, 0x2000
	s_nop 0
	global_load_lds_dwordx4 v[220:221], off
	s_barrier
	s_waitcnt lgkmcnt(0)
	s_setprio 1
	s_waitcnt lgkmcnt(0)
	v_mfma_f32_16x16x32_bf16 v[92:95], v[202:205], v[156:159], v[92:95]
	v_mfma_f32_16x16x32_bf16 v[88:91], v[210:213], v[156:159], v[88:91]
	v_mfma_f32_16x16x32_bf16 v[84:87], v[202:205], v[178:181], v[84:87]
	v_mfma_f32_16x16x32_bf16 v[80:83], v[210:213], v[178:181], v[80:83]
	v_mfma_f32_16x16x32_bf16 v[76:79], v[202:205], v[186:189], v[76:79]
	v_mfma_f32_16x16x32_bf16 v[72:75], v[210:213], v[186:189], v[72:75]
	v_mfma_f32_16x16x32_bf16 v[68:71], v[202:205], v[194:197], v[68:71]
	v_mfma_f32_16x16x32_bf16 v[64:67], v[210:213], v[194:197], v[64:67]
	v_mfma_f32_16x16x32_bf16 v[92:95], v[206:209], v[166:169], v[92:95]
	v_mfma_f32_16x16x32_bf16 v[88:91], v[214:217], v[166:169], v[88:91]
	v_mfma_f32_16x16x32_bf16 v[84:87], v[206:209], v[182:185], v[84:87]
	v_mfma_f32_16x16x32_bf16 v[80:83], v[214:217], v[182:185], v[80:83]
	v_mfma_f32_16x16x32_bf16 v[76:79], v[206:209], v[190:193], v[76:79]
	v_mfma_f32_16x16x32_bf16 v[72:75], v[214:217], v[190:193], v[72:75]
	v_mfma_f32_16x16x32_bf16 v[68:71], v[206:209], v[198:201], v[68:71]
	v_mfma_f32_16x16x32_bf16 v[64:67], v[214:217], v[198:201], v[64:67]
	s_setprio 0
	s_mov_b32 m0, s36
	v_lshl_add_u64 v[222:223], s[28:29], 0, v[130:131]
	s_barrier
	ds_read_b128 v[156:159], v164 offset:16384
	ds_read_b128 v[166:169], v164 offset:17408
	ds_read_b128 v[178:181], v164 offset:18432
	ds_read_b128 v[182:185], v164 offset:19456
	ds_read_b128 v[186:189], v164 offset:20480
	ds_read_b128 v[190:193], v164 offset:21504
	ds_read_b128 v[194:197], v164 offset:22528
	ds_read_b128 v[198:201], v164 offset:23552
	global_load_lds_dwordx4 v[222:223], off
	v_lshl_add_u64 v[224:225], s[28:29], 0, v[128:129]
	s_mov_b32 m0, s37
	s_nop 0
	global_load_lds_dwordx4 v[224:225], off
	s_barrier
	s_waitcnt lgkmcnt(0)
	s_setprio 1
	s_waitcnt lgkmcnt(0)
	v_mfma_f32_16x16x32_bf16 v[60:63], v[140:143], v[156:159], v[60:63]
	v_mfma_f32_16x16x32_bf16 v[56:59], v[148:151], v[156:159], v[56:59]
	v_mfma_f32_16x16x32_bf16 v[52:55], v[140:143], v[178:181], v[52:55]
	v_mfma_f32_16x16x32_bf16 v[48:51], v[148:151], v[178:181], v[48:51]
	v_mfma_f32_16x16x32_bf16 v[44:47], v[140:143], v[186:189], v[44:47]
	v_mfma_f32_16x16x32_bf16 v[40:43], v[148:151], v[186:189], v[40:43]
	v_mfma_f32_16x16x32_bf16 v[36:39], v[140:143], v[194:197], v[36:39]
	v_mfma_f32_16x16x32_bf16 v[32:35], v[148:151], v[194:197], v[32:35]
	v_mfma_f32_16x16x32_bf16 v[60:63], v[144:147], v[166:169], v[60:63]
	v_mfma_f32_16x16x32_bf16 v[56:59], v[152:155], v[166:169], v[56:59]
	v_mfma_f32_16x16x32_bf16 v[52:55], v[144:147], v[182:185], v[52:55]
	v_mfma_f32_16x16x32_bf16 v[48:51], v[152:155], v[182:185], v[48:51]
	v_mfma_f32_16x16x32_bf16 v[44:47], v[144:147], v[190:193], v[44:47]
	v_mfma_f32_16x16x32_bf16 v[40:43], v[152:155], v[190:193], v[40:43]
	v_mfma_f32_16x16x32_bf16 v[36:39], v[144:147], v[198:201], v[36:39]
	v_mfma_f32_16x16x32_bf16 v[32:35], v[152:155], v[198:201], v[32:35]
	s_setprio 0
	s_barrier
	s_add_u32 s62, s10, 0x20000
	s_addc_u32 s63, s11, 0
	s_add_i32 s33, s56, s35
	v_lshl_add_u64 v[140:141], s[62:63], 0, v[130:131]
	s_mov_b32 m0, s33
	s_nop 0
	global_load_lds_dwordx4 v[140:141], off
	v_lshl_add_u64 v[140:141], s[62:63], 0, v[128:129]
	s_add_i32 m0, s33, 0x2000
	s_nop 0
	global_load_lds_dwordx4 v[140:141], off
	s_waitcnt vmcnt(6)
	s_barrier
	s_setprio 1
	v_mfma_f32_16x16x32_bf16 v[28:31], v[202:205], v[156:159], v[28:31]
	v_mfma_f32_16x16x32_bf16 v[24:27], v[210:213], v[156:159], v[24:27]
	v_mfma_f32_16x16x32_bf16 v[20:23], v[202:205], v[178:181], v[20:23]
	v_mfma_f32_16x16x32_bf16 v[16:19], v[210:213], v[178:181], v[16:19]
	v_mfma_f32_16x16x32_bf16 v[12:15], v[202:205], v[186:189], v[12:15]
	v_mfma_f32_16x16x32_bf16 v[8:11], v[210:213], v[186:189], v[8:11]
	v_mfma_f32_16x16x32_bf16 v[4:7], v[202:205], v[194:197], v[4:7]
	v_mfma_f32_16x16x32_bf16 v[0:3], v[210:213], v[194:197], v[0:3]
	v_mfma_f32_16x16x32_bf16 v[28:31], v[206:209], v[166:169], v[28:31]
	v_mfma_f32_16x16x32_bf16 v[24:27], v[214:217], v[166:169], v[24:27]
	v_mfma_f32_16x16x32_bf16 v[20:23], v[206:209], v[182:185], v[20:23]
	v_mfma_f32_16x16x32_bf16 v[16:19], v[214:217], v[182:185], v[16:19]
	v_mfma_f32_16x16x32_bf16 v[12:15], v[206:209], v[190:193], v[12:15]
	v_mfma_f32_16x16x32_bf16 v[8:11], v[214:217], v[190:193], v[8:11]
	v_mfma_f32_16x16x32_bf16 v[4:7], v[206:209], v[198:201], v[4:7]
	v_mfma_f32_16x16x32_bf16 v[0:3], v[214:217], v[198:201], v[0:3]
	s_setprio 0
	s_add_i32 s33, 0, 0x18000
	v_add_u32_e32 v152, s33, v161
	s_barrier
	ds_read_b128 v[140:143], v152
	ds_read_b128 v[144:147], v152 offset:1024
	ds_read_b128 v[148:151], v152 offset:2048
	ds_read_b128 v[152:155], v152 offset:3072
	s_add_u32 s28, s28, 0x20000
	s_addc_u32 s29, s29, 0
	s_mov_b32 m0, s40
	v_lshl_add_u64 v[202:203], s[28:29], 0, v[130:131]
	ds_read_b128 v[156:159], v164 offset:32768
	ds_read_b128 v[166:169], v164 offset:33792
	ds_read_b128 v[178:181], v164 offset:34816
	ds_read_b128 v[182:185], v164 offset:35840
	ds_read_b128 v[186:189], v164 offset:36864
	ds_read_b128 v[190:193], v164 offset:37888
	ds_read_b128 v[194:197], v164 offset:38912
	ds_read_b128 v[198:201], v164 offset:39936
	global_load_lds_dwordx4 v[202:203], off
	v_lshl_add_u64 v[202:203], s[28:29], 0, v[128:129]
	s_mov_b32 m0, s41
	s_nop 0
	global_load_lds_dwordx4 v[202:203], off
	s_waitcnt lgkmcnt(8)
	s_barrier
	s_waitcnt lgkmcnt(0)
	s_setprio 1
	s_waitcnt lgkmcnt(0)
	v_mfma_f32_16x16x32_bf16 v[124:127], v[140:143], v[156:159], v[124:127]
	v_mfma_f32_16x16x32_bf16 v[120:123], v[148:151], v[156:159], v[120:123]
	v_mfma_f32_16x16x32_bf16 v[116:119], v[140:143], v[178:181], v[116:119]
	v_mfma_f32_16x16x32_bf16 v[112:115], v[148:151], v[178:181], v[112:115]
	v_mfma_f32_16x16x32_bf16 v[108:111], v[140:143], v[186:189], v[108:111]
	v_mfma_f32_16x16x32_bf16 v[104:107], v[148:151], v[186:189], v[104:107]
	v_mfma_f32_16x16x32_bf16 v[100:103], v[140:143], v[194:197], v[100:103]
	v_mfma_f32_16x16x32_bf16 v[96:99], v[148:151], v[194:197], v[96:99]
	v_mfma_f32_16x16x32_bf16 v[124:127], v[144:147], v[166:169], v[124:127]
	v_mfma_f32_16x16x32_bf16 v[120:123], v[152:155], v[166:169], v[120:123]
	v_mfma_f32_16x16x32_bf16 v[116:119], v[144:147], v[182:185], v[116:119]
	v_mfma_f32_16x16x32_bf16 v[112:115], v[152:155], v[182:185], v[112:115]
	v_mfma_f32_16x16x32_bf16 v[108:111], v[144:147], v[190:193], v[108:111]
	v_mfma_f32_16x16x32_bf16 v[104:107], v[152:155], v[190:193], v[104:107]
	v_mfma_f32_16x16x32_bf16 v[100:103], v[144:147], v[198:201], v[100:103]
	v_mfma_f32_16x16x32_bf16 v[96:99], v[152:155], v[198:201], v[96:99]
	s_setprio 0
	s_barrier
	s_add_i32 s28, 0, 0x1c000
	s_add_i32 s29, s33, s35
	v_add_u32_e32 v177, s28, v161
	v_lshl_add_u64 v[218:219], v[218:219], 0, s[16:17]
	s_mov_b32 m0, s29
	ds_read_b128 v[202:205], v177
	ds_read_b128 v[206:209], v177 offset:1024
	ds_read_b128 v[210:213], v177 offset:2048
	ds_read_b128 v[214:217], v177 offset:3072
	global_load_lds_dwordx4 v[218:219], off
	v_lshl_add_u64 v[218:219], v[220:221], 0, s[16:17]
	s_add_i32 m0, s29, 0x2000
	s_nop 0
	global_load_lds_dwordx4 v[218:219], off
	s_barrier
	s_waitcnt lgkmcnt(0)
	s_setprio 1
	s_waitcnt lgkmcnt(0)
	v_mfma_f32_16x16x32_bf16 v[92:95], v[202:205], v[156:159], v[92:95]
	v_mfma_f32_16x16x32_bf16 v[88:91], v[210:213], v[156:159], v[88:91]
	v_mfma_f32_16x16x32_bf16 v[84:87], v[202:205], v[178:181], v[84:87]
	v_mfma_f32_16x16x32_bf16 v[80:83], v[210:213], v[178:181], v[80:83]
	v_mfma_f32_16x16x32_bf16 v[76:79], v[202:205], v[186:189], v[76:79]
	v_mfma_f32_16x16x32_bf16 v[72:75], v[210:213], v[186:189], v[72:75]
	v_mfma_f32_16x16x32_bf16 v[68:71], v[202:205], v[194:197], v[68:71]
	v_mfma_f32_16x16x32_bf16 v[64:67], v[210:213], v[194:197], v[64:67]
	v_mfma_f32_16x16x32_bf16 v[92:95], v[206:209], v[166:169], v[92:95]
	v_mfma_f32_16x16x32_bf16 v[88:91], v[214:217], v[166:169], v[88:91]
	v_mfma_f32_16x16x32_bf16 v[84:87], v[206:209], v[182:185], v[84:87]
	v_mfma_f32_16x16x32_bf16 v[80:83], v[214:217], v[182:185], v[80:83]
	v_mfma_f32_16x16x32_bf16 v[76:79], v[206:209], v[190:193], v[76:79]
	v_mfma_f32_16x16x32_bf16 v[72:75], v[214:217], v[190:193], v[72:75]
	v_mfma_f32_16x16x32_bf16 v[68:71], v[206:209], v[198:201], v[68:71]
	v_mfma_f32_16x16x32_bf16 v[64:67], v[214:217], v[198:201], v[64:67]
	s_setprio 0
	s_mov_b32 m0, s47
	v_lshl_add_u64 v[218:219], v[222:223], 0, s[16:17]
	s_barrier
	ds_read_b128 v[156:159], v164 offset:49152
	ds_read_b128 v[166:169], v164 offset:50176
	ds_read_b128 v[178:181], v164 offset:51200
	ds_read_b128 v[182:185], v164 offset:52224
	ds_read_b128 v[186:189], v164 offset:53248
	ds_read_b128 v[190:193], v164 offset:54272
	ds_read_b128 v[194:197], v164 offset:55296
	ds_read_b128 v[198:201], v164 offset:56320
	global_load_lds_dwordx4 v[218:219], off
	v_lshl_add_u64 v[218:219], v[224:225], 0, s[16:17]
	s_mov_b32 m0, s52
	s_nop 0
	global_load_lds_dwordx4 v[218:219], off
	s_barrier
	s_waitcnt lgkmcnt(0)
	s_setprio 1
	s_waitcnt lgkmcnt(0)
	v_mfma_f32_16x16x32_bf16 v[60:63], v[140:143], v[156:159], v[60:63]
	v_mfma_f32_16x16x32_bf16 v[56:59], v[148:151], v[156:159], v[56:59]
	v_mfma_f32_16x16x32_bf16 v[52:55], v[140:143], v[178:181], v[52:55]
	v_mfma_f32_16x16x32_bf16 v[48:51], v[148:151], v[178:181], v[48:51]
	v_mfma_f32_16x16x32_bf16 v[44:47], v[140:143], v[186:189], v[44:47]
	v_mfma_f32_16x16x32_bf16 v[40:43], v[148:151], v[186:189], v[40:43]
	v_mfma_f32_16x16x32_bf16 v[36:39], v[140:143], v[194:197], v[36:39]
	v_mfma_f32_16x16x32_bf16 v[32:35], v[148:151], v[194:197], v[32:35]
	v_mfma_f32_16x16x32_bf16 v[60:63], v[144:147], v[166:169], v[60:63]
	v_mfma_f32_16x16x32_bf16 v[56:59], v[152:155], v[166:169], v[56:59]
	v_mfma_f32_16x16x32_bf16 v[52:55], v[144:147], v[182:185], v[52:55]
	v_mfma_f32_16x16x32_bf16 v[48:51], v[152:155], v[182:185], v[48:51]
	v_mfma_f32_16x16x32_bf16 v[44:47], v[144:147], v[190:193], v[44:47]
	v_mfma_f32_16x16x32_bf16 v[40:43], v[152:155], v[190:193], v[40:43]
	v_mfma_f32_16x16x32_bf16 v[36:39], v[144:147], v[198:201], v[36:39]
	v_mfma_f32_16x16x32_bf16 v[32:35], v[152:155], v[198:201], v[32:35]
	s_setprio 0
	s_barrier
	s_add_u32 s10, s10, 0x20080
	s_addc_u32 s11, s11, 0
	s_add_i32 s28, s28, s35
	v_lshl_add_u64 v[140:141], s[10:11], 0, v[130:131]
	s_mov_b32 m0, s28
	s_nop 0
	global_load_lds_dwordx4 v[140:141], off
	v_lshl_add_u64 v[140:141], s[10:11], 0, v[128:129]
	s_add_i32 m0, s28, 0x2000
	s_nop 0
	global_load_lds_dwordx4 v[140:141], off
	s_waitcnt vmcnt(6)
	s_barrier
	s_setprio 1
	v_mfma_f32_16x16x32_bf16 v[28:31], v[202:205], v[156:159], v[28:31]
	v_mfma_f32_16x16x32_bf16 v[24:27], v[210:213], v[156:159], v[24:27]
	v_mfma_f32_16x16x32_bf16 v[20:23], v[202:205], v[178:181], v[20:23]
	v_mfma_f32_16x16x32_bf16 v[16:19], v[210:213], v[178:181], v[16:19]
	v_mfma_f32_16x16x32_bf16 v[12:15], v[202:205], v[186:189], v[12:15]
	v_mfma_f32_16x16x32_bf16 v[8:11], v[210:213], v[186:189], v[8:11]
	v_mfma_f32_16x16x32_bf16 v[4:7], v[202:205], v[194:197], v[4:7]
	v_mfma_f32_16x16x32_bf16 v[0:3], v[210:213], v[194:197], v[0:3]
	v_mfma_f32_16x16x32_bf16 v[28:31], v[206:209], v[166:169], v[28:31]
	v_mfma_f32_16x16x32_bf16 v[24:27], v[214:217], v[166:169], v[24:27]
	v_mfma_f32_16x16x32_bf16 v[20:23], v[206:209], v[182:185], v[20:23]
	v_mfma_f32_16x16x32_bf16 v[16:19], v[214:217], v[182:185], v[16:19]
	v_mfma_f32_16x16x32_bf16 v[12:15], v[206:209], v[190:193], v[12:15]
	v_mfma_f32_16x16x32_bf16 v[8:11], v[214:217], v[190:193], v[8:11]
	v_mfma_f32_16x16x32_bf16 v[4:7], v[206:209], v[198:201], v[4:7]
	v_mfma_f32_16x16x32_bf16 v[0:3], v[214:217], v[198:201], v[0:3]
	s_setprio 0
	s_add_i32 s61, s61, 2
	s_add_u32 s59, s59, 0x100
	s_addc_u32 s60, s60, 0
	s_add_u32 s8, s8, 0x100
	s_addc_u32 s9, s9, 0
	s_cmp_gt_u32 s61, 5
	s_barrier
	s_cbranch_scc0 .LBB0_1177
	s_cmpk_gt_i32 s2, 0x5f
	s_cbranch_scc1 .Lglu_r1
	s_lshl_b32 s8, s6, 8
	v_add_u32_e32 v158, s8, v160
	v_lshl_or_b32 v159, s7, 8, v162
	v_lshlrev_b32_e32 v166, 10, v158
	v_lshl_add_u32 v166, v159, 1, v166
	global_load_dwordx2 v[178:179], v166, s[14:15]
	global_load_dwordx2 v[180:181], v166, s[14:15] offset:32
	global_load_dwordx2 v[182:183], v166, s[14:15] offset:256
	global_load_dwordx2 v[184:185], v166, s[14:15] offset:288
	v_add_u32_e32 v167, 0x4000, v166
	global_load_dwordx2 v[186:187], v167, s[14:15]
	global_load_dwordx2 v[188:189], v167, s[14:15] offset:32
	global_load_dwordx2 v[190:191], v167, s[14:15] offset:256
	global_load_dwordx2 v[192:193], v167, s[14:15] offset:288
	v_add_u32_e32 v167, 0x8000, v166
	global_load_dwordx2 v[194:195], v167, s[14:15]
	global_load_dwordx2 v[196:197], v167, s[14:15] offset:32
	global_load_dwordx2 v[198:199], v167, s[14:15] offset:256
	global_load_dwordx2 v[200:201], v167, s[14:15] offset:288
	v_add_u32_e32 v167, 0xc000, v166
	global_load_dwordx2 v[202:203], v167, s[14:15]
	global_load_dwordx2 v[204:205], v167, s[14:15] offset:32
	global_load_dwordx2 v[206:207], v167, s[14:15] offset:256
	global_load_dwordx2 v[208:209], v167, s[14:15] offset:288
	v_lshlrev_b32_e32 v168, 11, v158
	v_lshl_add_u32 v168, v159, 1, v168
	v_bfe_u32 v169, v162, 2, 2
	v_lshl_add_u32 v168, v169, 3, v168
	v_add_u32_e32 v168, 0xc99c400, v168
	v_and_b32_e32 v158, 15, v160
	v_and_b32_e32 v159, 1, v169
	v_lshrrev_b32_e32 v166, 1, v169
	v_lshl_or_b32 v159, v159, 1, v166
	v_xor_b32_e32 v166, 2, v159
	v_lshl_add_u32 v159, v159, 4, v158
	v_lshl_add_u32 v166, v166, 4, v158
	v_lshlrev_b32_e32 v159, 2, v159
	v_lshlrev_b32_e32 v166, 2, v166
	v_and_b32_e32 v167, 1, v169
	v_cmp_eq_u32_e64 s[8:9], 1, v167
	v_cmp_lt_u32_e64 s[10:11], 1, v169
	s_waitcnt vmcnt(15)
	v_mul_f32_e32 v124, 0xbfb8aa3b, v124
	v_mul_f32_e32 v125, 0xbfb8aa3b, v125
	v_mul_f32_e32 v126, 0xbfb8aa3b, v126
	v_mul_f32_e32 v127, 0xbfb8aa3b, v127
	v_exp_f32_e32 v124, v124
	v_exp_f32_e32 v125, v125
	v_exp_f32_e32 v126, v126
	v_exp_f32_e32 v127, v127
	v_lshlrev_b32_e32 v158, 16, v178
	v_and_b32_e32 v178, 0xffff0000, v178
	v_pk_add_f32 v[124:125], v[124:125], 1.0 op_sel_hi:[1,0]
	v_pk_add_f32 v[126:127], v[126:127], 1.0 op_sel_hi:[1,0]
	v_lshlrev_b32_e32 v167, 16, v179
	v_and_b32_e32 v179, 0xffff0000, v179
	v_div_scale_f32 v140, s[6:7], v124, v124, v158
	v_div_scale_f32 v141, s[6:7], v125, v125, v178
	v_rcp_f32_e32 v144, v140
	v_rcp_f32_e32 v145, v141
	v_div_scale_f32 v142, vcc, v158, v124, v158
	v_div_scale_f32 v143, s[6:7], v178, v125, v178
	v_fma_f32 v146, -v140, v144, 1.0
	v_fma_f32 v147, -v141, v145, 1.0
	v_fmac_f32_e32 v144, v146, v144
	v_fmac_f32_e32 v145, v147, v145
	v_mul_f32_e32 v148, v142, v144
	v_mul_f32_e32 v149, v143, v145
	v_fma_f32 v146, -v140, v148, v142
	v_fma_f32 v147, -v141, v149, v143
	v_fmac_f32_e32 v148, v146, v144
	v_fmac_f32_e32 v149, v147, v145
	v_fma_f32 v146, -v140, v148, v142
	v_fma_f32 v147, -v141, v149, v143
	v_div_fmas_f32 v146, v146, v144, v148
	s_mov_b64 vcc, s[6:7]
	v_div_fixup_f32 v124, v146, v124, v158
	s_nop 1
	v_div_fmas_f32 v147, v147, v145, v149
	v_div_fixup_f32 v125, v147, v125, v178
	v_div_scale_f32 v140, s[6:7], v126, v126, v167
	v_div_scale_f32 v141, s[6:7], v127, v127, v179
	v_rcp_f32_e32 v144, v140
	v_rcp_f32_e32 v145, v141
	v_div_scale_f32 v142, vcc, v167, v126, v167
	v_div_scale_f32 v143, s[6:7], v179, v127, v179
	v_fma_f32 v146, -v140, v144, 1.0
	v_fma_f32 v147, -v141, v145, 1.0
	v_fmac_f32_e32 v144, v146, v144
	v_fmac_f32_e32 v145, v147, v145
	v_mul_f32_e32 v148, v142, v144
	v_mul_f32_e32 v149, v143, v145
	v_fma_f32 v146, -v140, v148, v142
	v_fma_f32 v147, -v141, v149, v143
	v_fmac_f32_e32 v148, v146, v144
	v_fmac_f32_e32 v149, v147, v145
	v_fma_f32 v146, -v140, v148, v142
	v_fma_f32 v147, -v141, v149, v143
	v_div_fmas_f32 v146, v146, v144, v148
	s_mov_b64 vcc, s[6:7]
	v_div_fixup_f32 v126, v146, v126, v167
	s_nop 1
	v_div_fmas_f32 v147, v147, v145, v149
	v_div_fixup_f32 v127, v147, v127, v179
	v_cvt_pk_bf16_f32 v124, v124, v125
	v_cvt_pk_bf16_f32 v125, v126, v127
	s_waitcnt vmcnt(14)
	v_mul_f32_e32 v120, 0xbfb8aa3b, v120
	v_mul_f32_e32 v121, 0xbfb8aa3b, v121
	v_mul_f32_e32 v122, 0xbfb8aa3b, v122
	v_mul_f32_e32 v123, 0xbfb8aa3b, v123
	v_exp_f32_e32 v120, v120
	v_exp_f32_e32 v121, v121
	v_exp_f32_e32 v122, v122
	v_exp_f32_e32 v123, v123
	v_lshlrev_b32_e32 v158, 16, v180
	v_and_b32_e32 v180, 0xffff0000, v180
	v_pk_add_f32 v[120:121], v[120:121], 1.0 op_sel_hi:[1,0]
	v_pk_add_f32 v[122:123], v[122:123], 1.0 op_sel_hi:[1,0]
	v_lshlrev_b32_e32 v167, 16, v181
	v_and_b32_e32 v181, 0xffff0000, v181
	v_div_scale_f32 v140, s[6:7], v120, v120, v158
	v_div_scale_f32 v141, s[6:7], v121, v121, v180
	v_rcp_f32_e32 v144, v140
	v_rcp_f32_e32 v145, v141
	v_div_scale_f32 v142, vcc, v158, v120, v158
	v_div_scale_f32 v143, s[6:7], v180, v121, v180
	v_fma_f32 v146, -v140, v144, 1.0
	v_fma_f32 v147, -v141, v145, 1.0
	v_fmac_f32_e32 v144, v146, v144
	v_fmac_f32_e32 v145, v147, v145
	v_mul_f32_e32 v148, v142, v144
	v_mul_f32_e32 v149, v143, v145
	v_fma_f32 v146, -v140, v148, v142
	v_fma_f32 v147, -v141, v149, v143
	v_fmac_f32_e32 v148, v146, v144
	v_fmac_f32_e32 v149, v147, v145
	v_fma_f32 v146, -v140, v148, v142
	v_fma_f32 v147, -v141, v149, v143
	v_div_fmas_f32 v146, v146, v144, v148
	s_mov_b64 vcc, s[6:7]
	v_div_fixup_f32 v120, v146, v120, v158
	s_nop 1
	v_div_fmas_f32 v147, v147, v145, v149
	v_div_fixup_f32 v121, v147, v121, v180
	v_div_scale_f32 v140, s[6:7], v122, v122, v167
	v_div_scale_f32 v141, s[6:7], v123, v123, v181
	v_rcp_f32_e32 v144, v140
	v_rcp_f32_e32 v145, v141
	v_div_scale_f32 v142, vcc, v167, v122, v167
	v_div_scale_f32 v143, s[6:7], v181, v123, v181
	v_fma_f32 v146, -v140, v144, 1.0
	v_fma_f32 v147, -v141, v145, 1.0
	v_fmac_f32_e32 v144, v146, v144
	v_fmac_f32_e32 v145, v147, v145
	v_mul_f32_e32 v148, v142, v144
	v_mul_f32_e32 v149, v143, v145
	v_fma_f32 v146, -v140, v148, v142
	v_fma_f32 v147, -v141, v149, v143
	v_fmac_f32_e32 v148, v146, v144
	v_fmac_f32_e32 v149, v147, v145
	v_fma_f32 v146, -v140, v148, v142
	v_fma_f32 v147, -v141, v149, v143
	v_div_fmas_f32 v146, v146, v144, v148
	s_mov_b64 vcc, s[6:7]
	v_div_fixup_f32 v122, v146, v122, v167
	s_nop 1
	v_div_fmas_f32 v147, v147, v145, v149
	v_div_fixup_f32 v123, v147, v123, v181
	v_cvt_pk_bf16_f32 v120, v120, v121
	v_cvt_pk_bf16_f32 v121, v122, v123
	v_cndmask_b32_e64 v126, v124, v120, s[8:9]
	v_cndmask_b32_e64 v127, v125, v121, s[8:9]
	v_cndmask_b32_e64 v122, v120, v124, s[8:9]
	v_cndmask_b32_e64 v123, v121, v125, s[8:9]
	ds_permute_b32 v124, v159, v126
	ds_permute_b32 v125, v159, v127
	ds_permute_b32 v120, v166, v122
	ds_permute_b32 v121, v166, v123
	s_waitcnt vmcnt(13)
	v_mul_f32_e32 v92, 0xbfb8aa3b, v92
	v_mul_f32_e32 v93, 0xbfb8aa3b, v93
	v_mul_f32_e32 v94, 0xbfb8aa3b, v94
	v_mul_f32_e32 v95, 0xbfb8aa3b, v95
	v_exp_f32_e32 v92, v92
	v_exp_f32_e32 v93, v93
	v_exp_f32_e32 v94, v94
	v_exp_f32_e32 v95, v95
	v_lshlrev_b32_e32 v158, 16, v182
	v_and_b32_e32 v182, 0xffff0000, v182
	v_pk_add_f32 v[92:93], v[92:93], 1.0 op_sel_hi:[1,0]
	v_pk_add_f32 v[94:95], v[94:95], 1.0 op_sel_hi:[1,0]
	v_lshlrev_b32_e32 v167, 16, v183
	v_and_b32_e32 v183, 0xffff0000, v183
	v_div_scale_f32 v140, s[6:7], v92, v92, v158
	v_div_scale_f32 v141, s[6:7], v93, v93, v182
	v_rcp_f32_e32 v144, v140
	v_rcp_f32_e32 v145, v141
	v_div_scale_f32 v142, vcc, v158, v92, v158
	v_div_scale_f32 v143, s[6:7], v182, v93, v182
	v_fma_f32 v146, -v140, v144, 1.0
	v_fma_f32 v147, -v141, v145, 1.0
	v_fmac_f32_e32 v144, v146, v144
	v_fmac_f32_e32 v145, v147, v145
	v_mul_f32_e32 v148, v142, v144
	v_mul_f32_e32 v149, v143, v145
	v_fma_f32 v146, -v140, v148, v142
	v_fma_f32 v147, -v141, v149, v143
	v_fmac_f32_e32 v148, v146, v144
	v_fmac_f32_e32 v149, v147, v145
	v_fma_f32 v146, -v140, v148, v142
	v_fma_f32 v147, -v141, v149, v143
	v_div_fmas_f32 v146, v146, v144, v148
	s_mov_b64 vcc, s[6:7]
	v_div_fixup_f32 v92, v146, v92, v158
	s_nop 1
	v_div_fmas_f32 v147, v147, v145, v149
	v_div_fixup_f32 v93, v147, v93, v182
	v_div_scale_f32 v140, s[6:7], v94, v94, v167
	v_div_scale_f32 v141, s[6:7], v95, v95, v183
	v_rcp_f32_e32 v144, v140
	v_rcp_f32_e32 v145, v141
	v_div_scale_f32 v142, vcc, v167, v94, v167
	v_div_scale_f32 v143, s[6:7], v183, v95, v183
	v_fma_f32 v146, -v140, v144, 1.0
	v_fma_f32 v147, -v141, v145, 1.0
	v_fmac_f32_e32 v144, v146, v144
	v_fmac_f32_e32 v145, v147, v145
	v_mul_f32_e32 v148, v142, v144
	v_mul_f32_e32 v149, v143, v145
	v_fma_f32 v146, -v140, v148, v142
	v_fma_f32 v147, -v141, v149, v143
	v_fmac_f32_e32 v148, v146, v144
	v_fmac_f32_e32 v149, v147, v145
	v_fma_f32 v146, -v140, v148, v142
	v_fma_f32 v147, -v141, v149, v143
	v_div_fmas_f32 v146, v146, v144, v148
	s_mov_b64 vcc, s[6:7]
	v_div_fixup_f32 v94, v146, v94, v167
	s_nop 1
	v_div_fmas_f32 v147, v147, v145, v149
	v_div_fixup_f32 v95, v147, v95, v183
	v_cvt_pk_bf16_f32 v92, v92, v93
	v_cvt_pk_bf16_f32 v93, v94, v95
	s_waitcnt vmcnt(12)
	v_mul_f32_e32 v88, 0xbfb8aa3b, v88
	v_mul_f32_e32 v89, 0xbfb8aa3b, v89
	v_mul_f32_e32 v90, 0xbfb8aa3b, v90
	v_mul_f32_e32 v91, 0xbfb8aa3b, v91
	v_exp_f32_e32 v88, v88
	v_exp_f32_e32 v89, v89
	v_exp_f32_e32 v90, v90
	v_exp_f32_e32 v91, v91
	v_lshlrev_b32_e32 v158, 16, v184
	v_and_b32_e32 v184, 0xffff0000, v184
	v_pk_add_f32 v[88:89], v[88:89], 1.0 op_sel_hi:[1,0]
	v_pk_add_f32 v[90:91], v[90:91], 1.0 op_sel_hi:[1,0]
	v_lshlrev_b32_e32 v167, 16, v185
	v_and_b32_e32 v185, 0xffff0000, v185
	v_div_scale_f32 v140, s[6:7], v88, v88, v158
	v_div_scale_f32 v141, s[6:7], v89, v89, v184
	v_rcp_f32_e32 v144, v140
	v_rcp_f32_e32 v145, v141
	v_div_scale_f32 v142, vcc, v158, v88, v158
	v_div_scale_f32 v143, s[6:7], v184, v89, v184
	v_fma_f32 v146, -v140, v144, 1.0
	v_fma_f32 v147, -v141, v145, 1.0
	v_fmac_f32_e32 v144, v146, v144
	v_fmac_f32_e32 v145, v147, v145
	v_mul_f32_e32 v148, v142, v144
	v_mul_f32_e32 v149, v143, v145
	v_fma_f32 v146, -v140, v148, v142
	v_fma_f32 v147, -v141, v149, v143
	v_fmac_f32_e32 v148, v146, v144
	v_fmac_f32_e32 v149, v147, v145
	v_fma_f32 v146, -v140, v148, v142
	v_fma_f32 v147, -v141, v149, v143
	v_div_fmas_f32 v146, v146, v144, v148
	s_mov_b64 vcc, s[6:7]
	v_div_fixup_f32 v88, v146, v88, v158
	s_nop 1
	v_div_fmas_f32 v147, v147, v145, v149
	v_div_fixup_f32 v89, v147, v89, v184
	v_div_scale_f32 v140, s[6:7], v90, v90, v167
	v_div_scale_f32 v141, s[6:7], v91, v91, v185
	v_rcp_f32_e32 v144, v140
	v_rcp_f32_e32 v145, v141
	v_div_scale_f32 v142, vcc, v167, v90, v167
	v_div_scale_f32 v143, s[6:7], v185, v91, v185
	v_fma_f32 v146, -v140, v144, 1.0
	v_fma_f32 v147, -v141, v145, 1.0
	v_fmac_f32_e32 v144, v146, v144
	v_fmac_f32_e32 v145, v147, v145
	v_mul_f32_e32 v148, v142, v144
	v_mul_f32_e32 v149, v143, v145
	v_fma_f32 v146, -v140, v148, v142
	v_fma_f32 v147, -v141, v149, v143
	v_fmac_f32_e32 v148, v146, v144
	v_fmac_f32_e32 v149, v147, v145
	v_fma_f32 v146, -v140, v148, v142
	v_fma_f32 v147, -v141, v149, v143
	v_div_fmas_f32 v146, v146, v144, v148
	s_mov_b64 vcc, s[6:7]
	v_div_fixup_f32 v90, v146, v90, v167
	s_nop 1
	v_div_fmas_f32 v147, v147, v145, v149
	v_div_fixup_f32 v91, v147, v91, v185
	v_cvt_pk_bf16_f32 v88, v88, v89
	v_cvt_pk_bf16_f32 v89, v90, v91
	v_cndmask_b32_e64 v94, v92, v88, s[8:9]
	v_cndmask_b32_e64 v95, v93, v89, s[8:9]
	v_cndmask_b32_e64 v90, v88, v92, s[8:9]
	v_cndmask_b32_e64 v91, v89, v93, s[8:9]
	ds_permute_b32 v92, v159, v94
	ds_permute_b32 v93, v159, v95
	ds_permute_b32 v88, v166, v90
	ds_permute_b32 v89, v166, v91
	s_waitcnt lgkmcnt(4)
	v_cndmask_b32_e64 v126, v120, v124, s[10:11]
	v_cndmask_b32_e64 v127, v121, v125, s[10:11]
	v_cndmask_b32_e64 v124, v124, v120, s[10:11]
	v_cndmask_b32_e64 v125, v125, v121, s[10:11]
	global_store_dwordx4 v168, v[124:127], s[12:13]
	s_waitcnt vmcnt(12)
	v_mul_f32_e32 v116, 0xbfb8aa3b, v116
	v_mul_f32_e32 v117, 0xbfb8aa3b, v117
	v_mul_f32_e32 v118, 0xbfb8aa3b, v118
	v_mul_f32_e32 v119, 0xbfb8aa3b, v119
	v_exp_f32_e32 v116, v116
	v_exp_f32_e32 v117, v117
	v_exp_f32_e32 v118, v118
	v_exp_f32_e32 v119, v119
	v_lshlrev_b32_e32 v158, 16, v186
	v_and_b32_e32 v186, 0xffff0000, v186
	v_pk_add_f32 v[116:117], v[116:117], 1.0 op_sel_hi:[1,0]
	v_pk_add_f32 v[118:119], v[118:119], 1.0 op_sel_hi:[1,0]
	v_lshlrev_b32_e32 v167, 16, v187
	v_and_b32_e32 v187, 0xffff0000, v187
	v_div_scale_f32 v140, s[6:7], v116, v116, v158
	v_div_scale_f32 v141, s[6:7], v117, v117, v186
	v_rcp_f32_e32 v144, v140
	v_rcp_f32_e32 v145, v141
	v_div_scale_f32 v142, vcc, v158, v116, v158
	v_div_scale_f32 v143, s[6:7], v186, v117, v186
	v_fma_f32 v146, -v140, v144, 1.0
	v_fma_f32 v147, -v141, v145, 1.0
	v_fmac_f32_e32 v144, v146, v144
	v_fmac_f32_e32 v145, v147, v145
	v_mul_f32_e32 v148, v142, v144
	v_mul_f32_e32 v149, v143, v145
	v_fma_f32 v146, -v140, v148, v142
	v_fma_f32 v147, -v141, v149, v143
	v_fmac_f32_e32 v148, v146, v144
	v_fmac_f32_e32 v149, v147, v145
	v_fma_f32 v146, -v140, v148, v142
	v_fma_f32 v147, -v141, v149, v143
	v_div_fmas_f32 v146, v146, v144, v148
	s_mov_b64 vcc, s[6:7]
	v_div_fixup_f32 v116, v146, v116, v158
	s_nop 1
	v_div_fmas_f32 v147, v147, v145, v149
	v_div_fixup_f32 v117, v147, v117, v186
	v_div_scale_f32 v140, s[6:7], v118, v118, v167
	v_div_scale_f32 v141, s[6:7], v119, v119, v187
	v_rcp_f32_e32 v144, v140
	v_rcp_f32_e32 v145, v141
	v_div_scale_f32 v142, vcc, v167, v118, v167
	v_div_scale_f32 v143, s[6:7], v187, v119, v187
	v_fma_f32 v146, -v140, v144, 1.0
	v_fma_f32 v147, -v141, v145, 1.0
	v_fmac_f32_e32 v144, v146, v144
	v_fmac_f32_e32 v145, v147, v145
	v_mul_f32_e32 v148, v142, v144
	v_mul_f32_e32 v149, v143, v145
	v_fma_f32 v146, -v140, v148, v142
	v_fma_f32 v147, -v141, v149, v143
	v_fmac_f32_e32 v148, v146, v144
	v_fmac_f32_e32 v149, v147, v145
	v_fma_f32 v146, -v140, v148, v142
	v_fma_f32 v147, -v141, v149, v143
	v_div_fmas_f32 v146, v146, v144, v148
	s_mov_b64 vcc, s[6:7]
	v_div_fixup_f32 v118, v146, v118, v167
	s_nop 1
	v_div_fmas_f32 v147, v147, v145, v149
	v_div_fixup_f32 v119, v147, v119, v187
	v_cvt_pk_bf16_f32 v116, v116, v117
	v_cvt_pk_bf16_f32 v117, v118, v119
	s_waitcnt vmcnt(11)
	v_mul_f32_e32 v112, 0xbfb8aa3b, v112
	v_mul_f32_e32 v113, 0xbfb8aa3b, v113
	v_mul_f32_e32 v114, 0xbfb8aa3b, v114
	v_mul_f32_e32 v115, 0xbfb8aa3b, v115
	v_exp_f32_e32 v112, v112
	v_exp_f32_e32 v113, v113
	v_exp_f32_e32 v114, v114
	v_exp_f32_e32 v115, v115
	v_lshlrev_b32_e32 v158, 16, v188
	v_and_b32_e32 v188, 0xffff0000, v188
	v_pk_add_f32 v[112:113], v[112:113], 1.0 op_sel_hi:[1,0]
	v_pk_add_f32 v[114:115], v[114:115], 1.0 op_sel_hi:[1,0]
	v_lshlrev_b32_e32 v167, 16, v189
	v_and_b32_e32 v189, 0xffff0000, v189
	v_div_scale_f32 v140, s[6:7], v112, v112, v158
	v_div_scale_f32 v141, s[6:7], v113, v113, v188
	v_rcp_f32_e32 v144, v140
	v_rcp_f32_e32 v145, v141
	v_div_scale_f32 v142, vcc, v158, v112, v158
	v_div_scale_f32 v143, s[6:7], v188, v113, v188
	v_fma_f32 v146, -v140, v144, 1.0
	v_fma_f32 v147, -v141, v145, 1.0
	v_fmac_f32_e32 v144, v146, v144
	v_fmac_f32_e32 v145, v147, v145
	v_mul_f32_e32 v148, v142, v144
	v_mul_f32_e32 v149, v143, v145
	v_fma_f32 v146, -v140, v148, v142
	v_fma_f32 v147, -v141, v149, v143
	v_fmac_f32_e32 v148, v146, v144
	v_fmac_f32_e32 v149, v147, v145
	v_fma_f32 v146, -v140, v148, v142
	v_fma_f32 v147, -v141, v149, v143
	v_div_fmas_f32 v146, v146, v144, v148
	s_mov_b64 vcc, s[6:7]
	v_div_fixup_f32 v112, v146, v112, v158
	s_nop 1
	v_div_fmas_f32 v147, v147, v145, v149
	v_div_fixup_f32 v113, v147, v113, v188
	v_div_scale_f32 v140, s[6:7], v114, v114, v167
	v_div_scale_f32 v141, s[6:7], v115, v115, v189
	v_rcp_f32_e32 v144, v140
	v_rcp_f32_e32 v145, v141
	v_div_scale_f32 v142, vcc, v167, v114, v167
	v_div_scale_f32 v143, s[6:7], v189, v115, v189
	v_fma_f32 v146, -v140, v144, 1.0
	v_fma_f32 v147, -v141, v145, 1.0
	v_fmac_f32_e32 v144, v146, v144
	v_fmac_f32_e32 v145, v147, v145
	v_mul_f32_e32 v148, v142, v144
	v_mul_f32_e32 v149, v143, v145
	v_fma_f32 v146, -v140, v148, v142
	v_fma_f32 v147, -v141, v149, v143
	v_fmac_f32_e32 v148, v146, v144
	v_fmac_f32_e32 v149, v147, v145
	v_fma_f32 v146, -v140, v148, v142
	v_fma_f32 v147, -v141, v149, v143
	v_div_fmas_f32 v146, v146, v144, v148
	s_mov_b64 vcc, s[6:7]
	v_div_fixup_f32 v114, v146, v114, v167
	s_nop 1
	v_div_fmas_f32 v147, v147, v145, v149
	v_div_fixup_f32 v115, v147, v115, v189
	v_cvt_pk_bf16_f32 v112, v112, v113
	v_cvt_pk_bf16_f32 v113, v114, v115
	v_cndmask_b32_e64 v118, v116, v112, s[8:9]
	v_cndmask_b32_e64 v119, v117, v113, s[8:9]
	v_cndmask_b32_e64 v114, v112, v116, s[8:9]
	v_cndmask_b32_e64 v115, v113, v117, s[8:9]
	ds_permute_b32 v116, v159, v118
	ds_permute_b32 v117, v159, v119
	ds_permute_b32 v112, v166, v114
	ds_permute_b32 v113, v166, v115
	s_waitcnt lgkmcnt(4)
	v_cndmask_b32_e64 v94, v88, v92, s[10:11]
	v_cndmask_b32_e64 v95, v89, v93, s[10:11]
	v_cndmask_b32_e64 v92, v92, v88, s[10:11]
	v_cndmask_b32_e64 v93, v93, v89, s[10:11]
	v_add_u32_e32 v169, 0x100, v168
	global_store_dwordx4 v169, v[92:95], s[12:13]
	s_waitcnt vmcnt(11)
	v_mul_f32_e32 v84, 0xbfb8aa3b, v84
	v_mul_f32_e32 v85, 0xbfb8aa3b, v85
	v_mul_f32_e32 v86, 0xbfb8aa3b, v86
	v_mul_f32_e32 v87, 0xbfb8aa3b, v87
	v_exp_f32_e32 v84, v84
	v_exp_f32_e32 v85, v85
	v_exp_f32_e32 v86, v86
	v_exp_f32_e32 v87, v87
	v_lshlrev_b32_e32 v158, 16, v190
	v_and_b32_e32 v190, 0xffff0000, v190
	v_pk_add_f32 v[84:85], v[84:85], 1.0 op_sel_hi:[1,0]
	v_pk_add_f32 v[86:87], v[86:87], 1.0 op_sel_hi:[1,0]
	v_lshlrev_b32_e32 v167, 16, v191
	v_and_b32_e32 v191, 0xffff0000, v191
	v_div_scale_f32 v140, s[6:7], v84, v84, v158
	v_div_scale_f32 v141, s[6:7], v85, v85, v190
	v_rcp_f32_e32 v144, v140
	v_rcp_f32_e32 v145, v141
	v_div_scale_f32 v142, vcc, v158, v84, v158
	v_div_scale_f32 v143, s[6:7], v190, v85, v190
	v_fma_f32 v146, -v140, v144, 1.0
	v_fma_f32 v147, -v141, v145, 1.0
	v_fmac_f32_e32 v144, v146, v144
	v_fmac_f32_e32 v145, v147, v145
	v_mul_f32_e32 v148, v142, v144
	v_mul_f32_e32 v149, v143, v145
	v_fma_f32 v146, -v140, v148, v142
	v_fma_f32 v147, -v141, v149, v143
	v_fmac_f32_e32 v148, v146, v144
	v_fmac_f32_e32 v149, v147, v145
	v_fma_f32 v146, -v140, v148, v142
	v_fma_f32 v147, -v141, v149, v143
	v_div_fmas_f32 v146, v146, v144, v148
	s_mov_b64 vcc, s[6:7]
	v_div_fixup_f32 v84, v146, v84, v158
	s_nop 1
	v_div_fmas_f32 v147, v147, v145, v149
	v_div_fixup_f32 v85, v147, v85, v190
	v_div_scale_f32 v140, s[6:7], v86, v86, v167
	v_div_scale_f32 v141, s[6:7], v87, v87, v191
	v_rcp_f32_e32 v144, v140
	v_rcp_f32_e32 v145, v141
	v_div_scale_f32 v142, vcc, v167, v86, v167
	v_div_scale_f32 v143, s[6:7], v191, v87, v191
	v_fma_f32 v146, -v140, v144, 1.0
	v_fma_f32 v147, -v141, v145, 1.0
	v_fmac_f32_e32 v144, v146, v144
	v_fmac_f32_e32 v145, v147, v145
	v_mul_f32_e32 v148, v142, v144
	v_mul_f32_e32 v149, v143, v145
	v_fma_f32 v146, -v140, v148, v142
	v_fma_f32 v147, -v141, v149, v143
	v_fmac_f32_e32 v148, v146, v144
	v_fmac_f32_e32 v149, v147, v145
	v_fma_f32 v146, -v140, v148, v142
	v_fma_f32 v147, -v141, v149, v143
	v_div_fmas_f32 v146, v146, v144, v148
	s_mov_b64 vcc, s[6:7]
	v_div_fixup_f32 v86, v146, v86, v167
	s_nop 1
	v_div_fmas_f32 v147, v147, v145, v149
	v_div_fixup_f32 v87, v147, v87, v191
	v_cvt_pk_bf16_f32 v84, v84, v85
	v_cvt_pk_bf16_f32 v85, v86, v87
	s_waitcnt vmcnt(10)
	v_mul_f32_e32 v80, 0xbfb8aa3b, v80
	v_mul_f32_e32 v81, 0xbfb8aa3b, v81
	v_mul_f32_e32 v82, 0xbfb8aa3b, v82
	v_mul_f32_e32 v83, 0xbfb8aa3b, v83
	v_exp_f32_e32 v80, v80
	v_exp_f32_e32 v81, v81
	v_exp_f32_e32 v82, v82
	v_exp_f32_e32 v83, v83
	v_lshlrev_b32_e32 v158, 16, v192
	v_and_b32_e32 v192, 0xffff0000, v192
	v_pk_add_f32 v[80:81], v[80:81], 1.0 op_sel_hi:[1,0]
	v_pk_add_f32 v[82:83], v[82:83], 1.0 op_sel_hi:[1,0]
	v_lshlrev_b32_e32 v167, 16, v193
	v_and_b32_e32 v193, 0xffff0000, v193
	v_div_scale_f32 v140, s[6:7], v80, v80, v158
	v_div_scale_f32 v141, s[6:7], v81, v81, v192
	v_rcp_f32_e32 v144, v140
	v_rcp_f32_e32 v145, v141
	v_div_scale_f32 v142, vcc, v158, v80, v158
	v_div_scale_f32 v143, s[6:7], v192, v81, v192
	v_fma_f32 v146, -v140, v144, 1.0
	v_fma_f32 v147, -v141, v145, 1.0
	v_fmac_f32_e32 v144, v146, v144
	v_fmac_f32_e32 v145, v147, v145
	v_mul_f32_e32 v148, v142, v144
	v_mul_f32_e32 v149, v143, v145
	v_fma_f32 v146, -v140, v148, v142
	v_fma_f32 v147, -v141, v149, v143
	v_fmac_f32_e32 v148, v146, v144
	v_fmac_f32_e32 v149, v147, v145
	v_fma_f32 v146, -v140, v148, v142
	v_fma_f32 v147, -v141, v149, v143
	v_div_fmas_f32 v146, v146, v144, v148
	s_mov_b64 vcc, s[6:7]
	v_div_fixup_f32 v80, v146, v80, v158
	s_nop 1
	v_div_fmas_f32 v147, v147, v145, v149
	v_div_fixup_f32 v81, v147, v81, v192
	v_div_scale_f32 v140, s[6:7], v82, v82, v167
	v_div_scale_f32 v141, s[6:7], v83, v83, v193
	v_rcp_f32_e32 v144, v140
	v_rcp_f32_e32 v145, v141
	v_div_scale_f32 v142, vcc, v167, v82, v167
	v_div_scale_f32 v143, s[6:7], v193, v83, v193
	v_fma_f32 v146, -v140, v144, 1.0
	v_fma_f32 v147, -v141, v145, 1.0
	v_fmac_f32_e32 v144, v146, v144
	v_fmac_f32_e32 v145, v147, v145
	v_mul_f32_e32 v148, v142, v144
	v_mul_f32_e32 v149, v143, v145
	v_fma_f32 v146, -v140, v148, v142
	v_fma_f32 v147, -v141, v149, v143
	v_fmac_f32_e32 v148, v146, v144
	v_fmac_f32_e32 v149, v147, v145
	v_fma_f32 v146, -v140, v148, v142
	v_fma_f32 v147, -v141, v149, v143
	v_div_fmas_f32 v146, v146, v144, v148
	s_mov_b64 vcc, s[6:7]
	v_div_fixup_f32 v82, v146, v82, v167
	s_nop 1
	v_div_fmas_f32 v147, v147, v145, v149
	v_div_fixup_f32 v83, v147, v83, v193
	v_cvt_pk_bf16_f32 v80, v80, v81
	v_cvt_pk_bf16_f32 v81, v82, v83
	v_cndmask_b32_e64 v86, v84, v80, s[8:9]
	v_cndmask_b32_e64 v87, v85, v81, s[8:9]
	v_cndmask_b32_e64 v82, v80, v84, s[8:9]
	v_cndmask_b32_e64 v83, v81, v85, s[8:9]
	ds_permute_b32 v84, v159, v86
	ds_permute_b32 v85, v159, v87
	ds_permute_b32 v80, v166, v82
	ds_permute_b32 v81, v166, v83
	s_waitcnt lgkmcnt(4)
	v_cndmask_b32_e64 v118, v112, v116, s[10:11]
	v_cndmask_b32_e64 v119, v113, v117, s[10:11]
	v_cndmask_b32_e64 v116, v116, v112, s[10:11]
	v_cndmask_b32_e64 v117, v117, v113, s[10:11]
	v_add_u32_e32 v169, 0x8000, v168
	global_store_dwordx4 v169, v[116:119], s[12:13]
	s_waitcnt vmcnt(10)
	v_mul_f32_e32 v108, 0xbfb8aa3b, v108
	v_mul_f32_e32 v109, 0xbfb8aa3b, v109
	v_mul_f32_e32 v110, 0xbfb8aa3b, v110
	v_mul_f32_e32 v111, 0xbfb8aa3b, v111
	v_exp_f32_e32 v108, v108
	v_exp_f32_e32 v109, v109
	v_exp_f32_e32 v110, v110
	v_exp_f32_e32 v111, v111
	v_lshlrev_b32_e32 v158, 16, v194
	v_and_b32_e32 v194, 0xffff0000, v194
	v_pk_add_f32 v[108:109], v[108:109], 1.0 op_sel_hi:[1,0]
	v_pk_add_f32 v[110:111], v[110:111], 1.0 op_sel_hi:[1,0]
	v_lshlrev_b32_e32 v167, 16, v195
	v_and_b32_e32 v195, 0xffff0000, v195
	v_div_scale_f32 v140, s[6:7], v108, v108, v158
	v_div_scale_f32 v141, s[6:7], v109, v109, v194
	v_rcp_f32_e32 v144, v140
	v_rcp_f32_e32 v145, v141
	v_div_scale_f32 v142, vcc, v158, v108, v158
	v_div_scale_f32 v143, s[6:7], v194, v109, v194
	v_fma_f32 v146, -v140, v144, 1.0
	v_fma_f32 v147, -v141, v145, 1.0
	v_fmac_f32_e32 v144, v146, v144
	v_fmac_f32_e32 v145, v147, v145
	v_mul_f32_e32 v148, v142, v144
	v_mul_f32_e32 v149, v143, v145
	v_fma_f32 v146, -v140, v148, v142
	v_fma_f32 v147, -v141, v149, v143
	v_fmac_f32_e32 v148, v146, v144
	v_fmac_f32_e32 v149, v147, v145
	v_fma_f32 v146, -v140, v148, v142
	v_fma_f32 v147, -v141, v149, v143
	v_div_fmas_f32 v146, v146, v144, v148
	s_mov_b64 vcc, s[6:7]
	v_div_fixup_f32 v108, v146, v108, v158
	s_nop 1
	v_div_fmas_f32 v147, v147, v145, v149
	v_div_fixup_f32 v109, v147, v109, v194
	v_div_scale_f32 v140, s[6:7], v110, v110, v167
	v_div_scale_f32 v141, s[6:7], v111, v111, v195
	v_rcp_f32_e32 v144, v140
	v_rcp_f32_e32 v145, v141
	v_div_scale_f32 v142, vcc, v167, v110, v167
	v_div_scale_f32 v143, s[6:7], v195, v111, v195
	v_fma_f32 v146, -v140, v144, 1.0
	v_fma_f32 v147, -v141, v145, 1.0
	v_fmac_f32_e32 v144, v146, v144
	v_fmac_f32_e32 v145, v147, v145
	v_mul_f32_e32 v148, v142, v144
	v_mul_f32_e32 v149, v143, v145
	v_fma_f32 v146, -v140, v148, v142
	v_fma_f32 v147, -v141, v149, v143
	v_fmac_f32_e32 v148, v146, v144
	v_fmac_f32_e32 v149, v147, v145
	v_fma_f32 v146, -v140, v148, v142
	v_fma_f32 v147, -v141, v149, v143
	v_div_fmas_f32 v146, v146, v144, v148
	s_mov_b64 vcc, s[6:7]
	v_div_fixup_f32 v110, v146, v110, v167
	s_nop 1
	v_div_fmas_f32 v147, v147, v145, v149
	v_div_fixup_f32 v111, v147, v111, v195
	v_cvt_pk_bf16_f32 v108, v108, v109
	v_cvt_pk_bf16_f32 v109, v110, v111
	s_waitcnt vmcnt(9)
	v_mul_f32_e32 v104, 0xbfb8aa3b, v104
	v_mul_f32_e32 v105, 0xbfb8aa3b, v105
	v_mul_f32_e32 v106, 0xbfb8aa3b, v106
	v_mul_f32_e32 v107, 0xbfb8aa3b, v107
	v_exp_f32_e32 v104, v104
	v_exp_f32_e32 v105, v105
	v_exp_f32_e32 v106, v106
	v_exp_f32_e32 v107, v107
	v_lshlrev_b32_e32 v158, 16, v196
	v_and_b32_e32 v196, 0xffff0000, v196
	v_pk_add_f32 v[104:105], v[104:105], 1.0 op_sel_hi:[1,0]
	v_pk_add_f32 v[106:107], v[106:107], 1.0 op_sel_hi:[1,0]
	v_lshlrev_b32_e32 v167, 16, v197
	v_and_b32_e32 v197, 0xffff0000, v197
	v_div_scale_f32 v140, s[6:7], v104, v104, v158
	v_div_scale_f32 v141, s[6:7], v105, v105, v196
	v_rcp_f32_e32 v144, v140
	v_rcp_f32_e32 v145, v141
	v_div_scale_f32 v142, vcc, v158, v104, v158
	v_div_scale_f32 v143, s[6:7], v196, v105, v196
	v_fma_f32 v146, -v140, v144, 1.0
	v_fma_f32 v147, -v141, v145, 1.0
	v_fmac_f32_e32 v144, v146, v144
	v_fmac_f32_e32 v145, v147, v145
	v_mul_f32_e32 v148, v142, v144
	v_mul_f32_e32 v149, v143, v145
	v_fma_f32 v146, -v140, v148, v142
	v_fma_f32 v147, -v141, v149, v143
	v_fmac_f32_e32 v148, v146, v144
	v_fmac_f32_e32 v149, v147, v145
	v_fma_f32 v146, -v140, v148, v142
	v_fma_f32 v147, -v141, v149, v143
	v_div_fmas_f32 v146, v146, v144, v148
	s_mov_b64 vcc, s[6:7]
	v_div_fixup_f32 v104, v146, v104, v158
	s_nop 1
	v_div_fmas_f32 v147, v147, v145, v149
	v_div_fixup_f32 v105, v147, v105, v196
	v_div_scale_f32 v140, s[6:7], v106, v106, v167
	v_div_scale_f32 v141, s[6:7], v107, v107, v197
	v_rcp_f32_e32 v144, v140
	v_rcp_f32_e32 v145, v141
	v_div_scale_f32 v142, vcc, v167, v106, v167
	v_div_scale_f32 v143, s[6:7], v197, v107, v197
	v_fma_f32 v146, -v140, v144, 1.0
	v_fma_f32 v147, -v141, v145, 1.0
	v_fmac_f32_e32 v144, v146, v144
	v_fmac_f32_e32 v145, v147, v145
	v_mul_f32_e32 v148, v142, v144
	v_mul_f32_e32 v149, v143, v145
	v_fma_f32 v146, -v140, v148, v142
	v_fma_f32 v147, -v141, v149, v143
	v_fmac_f32_e32 v148, v146, v144
	v_fmac_f32_e32 v149, v147, v145
	v_fma_f32 v146, -v140, v148, v142
	v_fma_f32 v147, -v141, v149, v143
	v_div_fmas_f32 v146, v146, v144, v148
	s_mov_b64 vcc, s[6:7]
	v_div_fixup_f32 v106, v146, v106, v167
	s_nop 1
	v_div_fmas_f32 v147, v147, v145, v149
	v_div_fixup_f32 v107, v147, v107, v197
	v_cvt_pk_bf16_f32 v104, v104, v105
	v_cvt_pk_bf16_f32 v105, v106, v107
	v_cndmask_b32_e64 v110, v108, v104, s[8:9]
	v_cndmask_b32_e64 v111, v109, v105, s[8:9]
	v_cndmask_b32_e64 v106, v104, v108, s[8:9]
	v_cndmask_b32_e64 v107, v105, v109, s[8:9]
	ds_permute_b32 v108, v159, v110
	ds_permute_b32 v109, v159, v111
	ds_permute_b32 v104, v166, v106
	ds_permute_b32 v105, v166, v107
	s_waitcnt lgkmcnt(4)
	v_cndmask_b32_e64 v86, v80, v84, s[10:11]
	v_cndmask_b32_e64 v87, v81, v85, s[10:11]
	v_cndmask_b32_e64 v84, v84, v80, s[10:11]
	v_cndmask_b32_e64 v85, v85, v81, s[10:11]
	v_add_u32_e32 v169, 0x8100, v168
	global_store_dwordx4 v169, v[84:87], s[12:13]
	s_waitcnt vmcnt(9)
	v_mul_f32_e32 v76, 0xbfb8aa3b, v76
	v_mul_f32_e32 v77, 0xbfb8aa3b, v77
	v_mul_f32_e32 v78, 0xbfb8aa3b, v78
	v_mul_f32_e32 v79, 0xbfb8aa3b, v79
	v_exp_f32_e32 v76, v76
	v_exp_f32_e32 v77, v77
	v_exp_f32_e32 v78, v78
	v_exp_f32_e32 v79, v79
	v_lshlrev_b32_e32 v158, 16, v198
	v_and_b32_e32 v198, 0xffff0000, v198
	v_pk_add_f32 v[76:77], v[76:77], 1.0 op_sel_hi:[1,0]
	v_pk_add_f32 v[78:79], v[78:79], 1.0 op_sel_hi:[1,0]
	v_lshlrev_b32_e32 v167, 16, v199
	v_and_b32_e32 v199, 0xffff0000, v199
	v_div_scale_f32 v140, s[6:7], v76, v76, v158
	v_div_scale_f32 v141, s[6:7], v77, v77, v198
	v_rcp_f32_e32 v144, v140
	v_rcp_f32_e32 v145, v141
	v_div_scale_f32 v142, vcc, v158, v76, v158
	v_div_scale_f32 v143, s[6:7], v198, v77, v198
	v_fma_f32 v146, -v140, v144, 1.0
	v_fma_f32 v147, -v141, v145, 1.0
	v_fmac_f32_e32 v144, v146, v144
	v_fmac_f32_e32 v145, v147, v145
	v_mul_f32_e32 v148, v142, v144
	v_mul_f32_e32 v149, v143, v145
	v_fma_f32 v146, -v140, v148, v142
	v_fma_f32 v147, -v141, v149, v143
	v_fmac_f32_e32 v148, v146, v144
	v_fmac_f32_e32 v149, v147, v145
	v_fma_f32 v146, -v140, v148, v142
	v_fma_f32 v147, -v141, v149, v143
	v_div_fmas_f32 v146, v146, v144, v148
	s_mov_b64 vcc, s[6:7]
	v_div_fixup_f32 v76, v146, v76, v158
	s_nop 1
	v_div_fmas_f32 v147, v147, v145, v149
	v_div_fixup_f32 v77, v147, v77, v198
	v_div_scale_f32 v140, s[6:7], v78, v78, v167
	v_div_scale_f32 v141, s[6:7], v79, v79, v199
	v_rcp_f32_e32 v144, v140
	v_rcp_f32_e32 v145, v141
	v_div_scale_f32 v142, vcc, v167, v78, v167
	v_div_scale_f32 v143, s[6:7], v199, v79, v199
	v_fma_f32 v146, -v140, v144, 1.0
	v_fma_f32 v147, -v141, v145, 1.0
	v_fmac_f32_e32 v144, v146, v144
	v_fmac_f32_e32 v145, v147, v145
	v_mul_f32_e32 v148, v142, v144
	v_mul_f32_e32 v149, v143, v145
	v_fma_f32 v146, -v140, v148, v142
	v_fma_f32 v147, -v141, v149, v143
	v_fmac_f32_e32 v148, v146, v144
	v_fmac_f32_e32 v149, v147, v145
	v_fma_f32 v146, -v140, v148, v142
	v_fma_f32 v147, -v141, v149, v143
	v_div_fmas_f32 v146, v146, v144, v148
	s_mov_b64 vcc, s[6:7]
	v_div_fixup_f32 v78, v146, v78, v167
	s_nop 1
	v_div_fmas_f32 v147, v147, v145, v149
	v_div_fixup_f32 v79, v147, v79, v199
	v_cvt_pk_bf16_f32 v76, v76, v77
	v_cvt_pk_bf16_f32 v77, v78, v79
	s_waitcnt vmcnt(8)
	v_mul_f32_e32 v72, 0xbfb8aa3b, v72
	v_mul_f32_e32 v73, 0xbfb8aa3b, v73
	v_mul_f32_e32 v74, 0xbfb8aa3b, v74
	v_mul_f32_e32 v75, 0xbfb8aa3b, v75
	v_exp_f32_e32 v72, v72
	v_exp_f32_e32 v73, v73
	v_exp_f32_e32 v74, v74
	v_exp_f32_e32 v75, v75
	v_lshlrev_b32_e32 v158, 16, v200
	v_and_b32_e32 v200, 0xffff0000, v200
	v_pk_add_f32 v[72:73], v[72:73], 1.0 op_sel_hi:[1,0]
	v_pk_add_f32 v[74:75], v[74:75], 1.0 op_sel_hi:[1,0]
	v_lshlrev_b32_e32 v167, 16, v201
	v_and_b32_e32 v201, 0xffff0000, v201
	v_div_scale_f32 v140, s[6:7], v72, v72, v158
	v_div_scale_f32 v141, s[6:7], v73, v73, v200
	v_rcp_f32_e32 v144, v140
	v_rcp_f32_e32 v145, v141
	v_div_scale_f32 v142, vcc, v158, v72, v158
	v_div_scale_f32 v143, s[6:7], v200, v73, v200
	v_fma_f32 v146, -v140, v144, 1.0
	v_fma_f32 v147, -v141, v145, 1.0
	v_fmac_f32_e32 v144, v146, v144
	v_fmac_f32_e32 v145, v147, v145
	v_mul_f32_e32 v148, v142, v144
	v_mul_f32_e32 v149, v143, v145
	v_fma_f32 v146, -v140, v148, v142
	v_fma_f32 v147, -v141, v149, v143
	v_fmac_f32_e32 v148, v146, v144
	v_fmac_f32_e32 v149, v147, v145
	v_fma_f32 v146, -v140, v148, v142
	v_fma_f32 v147, -v141, v149, v143
	v_div_fmas_f32 v146, v146, v144, v148
	s_mov_b64 vcc, s[6:7]
	v_div_fixup_f32 v72, v146, v72, v158
	s_nop 1
	v_div_fmas_f32 v147, v147, v145, v149
	v_div_fixup_f32 v73, v147, v73, v200
	v_div_scale_f32 v140, s[6:7], v74, v74, v167
	v_div_scale_f32 v141, s[6:7], v75, v75, v201
	v_rcp_f32_e32 v144, v140
	v_rcp_f32_e32 v145, v141
	v_div_scale_f32 v142, vcc, v167, v74, v167
	v_div_scale_f32 v143, s[6:7], v201, v75, v201
	v_fma_f32 v146, -v140, v144, 1.0
	v_fma_f32 v147, -v141, v145, 1.0
	v_fmac_f32_e32 v144, v146, v144
	v_fmac_f32_e32 v145, v147, v145
	v_mul_f32_e32 v148, v142, v144
	v_mul_f32_e32 v149, v143, v145
	v_fma_f32 v146, -v140, v148, v142
	v_fma_f32 v147, -v141, v149, v143
	v_fmac_f32_e32 v148, v146, v144
	v_fmac_f32_e32 v149, v147, v145
	v_fma_f32 v146, -v140, v148, v142
	v_fma_f32 v147, -v141, v149, v143
	v_div_fmas_f32 v146, v146, v144, v148
	s_mov_b64 vcc, s[6:7]
	v_div_fixup_f32 v74, v146, v74, v167
	s_nop 1
	v_div_fmas_f32 v147, v147, v145, v149
	v_div_fixup_f32 v75, v147, v75, v201
	v_cvt_pk_bf16_f32 v72, v72, v73
	v_cvt_pk_bf16_f32 v73, v74, v75
	v_cndmask_b32_e64 v78, v76, v72, s[8:9]
	v_cndmask_b32_e64 v79, v77, v73, s[8:9]
	v_cndmask_b32_e64 v74, v72, v76, s[8:9]
	v_cndmask_b32_e64 v75, v73, v77, s[8:9]
	ds_permute_b32 v76, v159, v78
	ds_permute_b32 v77, v159, v79
	ds_permute_b32 v72, v166, v74
	ds_permute_b32 v73, v166, v75
	s_waitcnt lgkmcnt(4)
	v_cndmask_b32_e64 v110, v104, v108, s[10:11]
	v_cndmask_b32_e64 v111, v105, v109, s[10:11]
	v_cndmask_b32_e64 v108, v108, v104, s[10:11]
	v_cndmask_b32_e64 v109, v109, v105, s[10:11]
	v_add_u32_e32 v169, 0x10000, v168
	global_store_dwordx4 v169, v[108:111], s[12:13]
	s_waitcnt vmcnt(8)
	v_mul_f32_e32 v100, 0xbfb8aa3b, v100
	v_mul_f32_e32 v101, 0xbfb8aa3b, v101
	v_mul_f32_e32 v102, 0xbfb8aa3b, v102
	v_mul_f32_e32 v103, 0xbfb8aa3b, v103
	v_exp_f32_e32 v100, v100
	v_exp_f32_e32 v101, v101
	v_exp_f32_e32 v102, v102
	v_exp_f32_e32 v103, v103
	v_lshlrev_b32_e32 v158, 16, v202
	v_and_b32_e32 v202, 0xffff0000, v202
	v_pk_add_f32 v[100:101], v[100:101], 1.0 op_sel_hi:[1,0]
	v_pk_add_f32 v[102:103], v[102:103], 1.0 op_sel_hi:[1,0]
	v_lshlrev_b32_e32 v167, 16, v203
	v_and_b32_e32 v203, 0xffff0000, v203
	v_div_scale_f32 v140, s[6:7], v100, v100, v158
	v_div_scale_f32 v141, s[6:7], v101, v101, v202
	v_rcp_f32_e32 v144, v140
	v_rcp_f32_e32 v145, v141
	v_div_scale_f32 v142, vcc, v158, v100, v158
	v_div_scale_f32 v143, s[6:7], v202, v101, v202
	v_fma_f32 v146, -v140, v144, 1.0
	v_fma_f32 v147, -v141, v145, 1.0
	v_fmac_f32_e32 v144, v146, v144
	v_fmac_f32_e32 v145, v147, v145
	v_mul_f32_e32 v148, v142, v144
	v_mul_f32_e32 v149, v143, v145
	v_fma_f32 v146, -v140, v148, v142
	v_fma_f32 v147, -v141, v149, v143
	v_fmac_f32_e32 v148, v146, v144
	v_fmac_f32_e32 v149, v147, v145
	v_fma_f32 v146, -v140, v148, v142
	v_fma_f32 v147, -v141, v149, v143
	v_div_fmas_f32 v146, v146, v144, v148
	s_mov_b64 vcc, s[6:7]
	v_div_fixup_f32 v100, v146, v100, v158
	s_nop 1
	v_div_fmas_f32 v147, v147, v145, v149
	v_div_fixup_f32 v101, v147, v101, v202
	v_div_scale_f32 v140, s[6:7], v102, v102, v167
	v_div_scale_f32 v141, s[6:7], v103, v103, v203
	v_rcp_f32_e32 v144, v140
	v_rcp_f32_e32 v145, v141
	v_div_scale_f32 v142, vcc, v167, v102, v167
	v_div_scale_f32 v143, s[6:7], v203, v103, v203
	v_fma_f32 v146, -v140, v144, 1.0
	v_fma_f32 v147, -v141, v145, 1.0
	v_fmac_f32_e32 v144, v146, v144
	v_fmac_f32_e32 v145, v147, v145
	v_mul_f32_e32 v148, v142, v144
	v_mul_f32_e32 v149, v143, v145
	v_fma_f32 v146, -v140, v148, v142
	v_fma_f32 v147, -v141, v149, v143
	v_fmac_f32_e32 v148, v146, v144
	v_fmac_f32_e32 v149, v147, v145
	v_fma_f32 v146, -v140, v148, v142
	v_fma_f32 v147, -v141, v149, v143
	v_div_fmas_f32 v146, v146, v144, v148
	s_mov_b64 vcc, s[6:7]
	v_div_fixup_f32 v102, v146, v102, v167
	s_nop 1
	v_div_fmas_f32 v147, v147, v145, v149
	v_div_fixup_f32 v103, v147, v103, v203
	v_cvt_pk_bf16_f32 v100, v100, v101
	v_cvt_pk_bf16_f32 v101, v102, v103
	s_waitcnt vmcnt(7)
	v_mul_f32_e32 v96, 0xbfb8aa3b, v96
	v_mul_f32_e32 v97, 0xbfb8aa3b, v97
	v_mul_f32_e32 v98, 0xbfb8aa3b, v98
	v_mul_f32_e32 v99, 0xbfb8aa3b, v99
	v_exp_f32_e32 v96, v96
	v_exp_f32_e32 v97, v97
	v_exp_f32_e32 v98, v98
	v_exp_f32_e32 v99, v99
	v_lshlrev_b32_e32 v158, 16, v204
	v_and_b32_e32 v204, 0xffff0000, v204
	v_pk_add_f32 v[96:97], v[96:97], 1.0 op_sel_hi:[1,0]
	v_pk_add_f32 v[98:99], v[98:99], 1.0 op_sel_hi:[1,0]
	v_lshlrev_b32_e32 v167, 16, v205
	v_and_b32_e32 v205, 0xffff0000, v205
	v_div_scale_f32 v140, s[6:7], v96, v96, v158
	v_div_scale_f32 v141, s[6:7], v97, v97, v204
	v_rcp_f32_e32 v144, v140
	v_rcp_f32_e32 v145, v141
	v_div_scale_f32 v142, vcc, v158, v96, v158
	v_div_scale_f32 v143, s[6:7], v204, v97, v204
	v_fma_f32 v146, -v140, v144, 1.0
	v_fma_f32 v147, -v141, v145, 1.0
	v_fmac_f32_e32 v144, v146, v144
	v_fmac_f32_e32 v145, v147, v145
	v_mul_f32_e32 v148, v142, v144
	v_mul_f32_e32 v149, v143, v145
	v_fma_f32 v146, -v140, v148, v142
	v_fma_f32 v147, -v141, v149, v143
	v_fmac_f32_e32 v148, v146, v144
	v_fmac_f32_e32 v149, v147, v145
	v_fma_f32 v146, -v140, v148, v142
	v_fma_f32 v147, -v141, v149, v143
	v_div_fmas_f32 v146, v146, v144, v148
	s_mov_b64 vcc, s[6:7]
	v_div_fixup_f32 v96, v146, v96, v158
	s_nop 1
	v_div_fmas_f32 v147, v147, v145, v149
	v_div_fixup_f32 v97, v147, v97, v204
	v_div_scale_f32 v140, s[6:7], v98, v98, v167
	v_div_scale_f32 v141, s[6:7], v99, v99, v205
	v_rcp_f32_e32 v144, v140
	v_rcp_f32_e32 v145, v141
	v_div_scale_f32 v142, vcc, v167, v98, v167
	v_div_scale_f32 v143, s[6:7], v205, v99, v205
	v_fma_f32 v146, -v140, v144, 1.0
	v_fma_f32 v147, -v141, v145, 1.0
	v_fmac_f32_e32 v144, v146, v144
	v_fmac_f32_e32 v145, v147, v145
	v_mul_f32_e32 v148, v142, v144
	v_mul_f32_e32 v149, v143, v145
	v_fma_f32 v146, -v140, v148, v142
	v_fma_f32 v147, -v141, v149, v143
	v_fmac_f32_e32 v148, v146, v144
	v_fmac_f32_e32 v149, v147, v145
	v_fma_f32 v146, -v140, v148, v142
	v_fma_f32 v147, -v141, v149, v143
	v_div_fmas_f32 v146, v146, v144, v148
	s_mov_b64 vcc, s[6:7]
	v_div_fixup_f32 v98, v146, v98, v167
	s_nop 1
	v_div_fmas_f32 v147, v147, v145, v149
	v_div_fixup_f32 v99, v147, v99, v205
	v_cvt_pk_bf16_f32 v96, v96, v97
	v_cvt_pk_bf16_f32 v97, v98, v99
	v_cndmask_b32_e64 v102, v100, v96, s[8:9]
	v_cndmask_b32_e64 v103, v101, v97, s[8:9]
	v_cndmask_b32_e64 v98, v96, v100, s[8:9]
	v_cndmask_b32_e64 v99, v97, v101, s[8:9]
	ds_permute_b32 v100, v159, v102
	ds_permute_b32 v101, v159, v103
	ds_permute_b32 v96, v166, v98
	ds_permute_b32 v97, v166, v99
	s_waitcnt lgkmcnt(4)
	v_cndmask_b32_e64 v78, v72, v76, s[10:11]
	v_cndmask_b32_e64 v79, v73, v77, s[10:11]
	v_cndmask_b32_e64 v76, v76, v72, s[10:11]
	v_cndmask_b32_e64 v77, v77, v73, s[10:11]
	v_add_u32_e32 v169, 0x10100, v168
	global_store_dwordx4 v169, v[76:79], s[12:13]
	s_waitcnt vmcnt(7)
	v_mul_f32_e32 v68, 0xbfb8aa3b, v68
	v_mul_f32_e32 v69, 0xbfb8aa3b, v69
	v_mul_f32_e32 v70, 0xbfb8aa3b, v70
	v_mul_f32_e32 v71, 0xbfb8aa3b, v71
	v_exp_f32_e32 v68, v68
	v_exp_f32_e32 v69, v69
	v_exp_f32_e32 v70, v70
	v_exp_f32_e32 v71, v71
	v_lshlrev_b32_e32 v158, 16, v206
	v_and_b32_e32 v206, 0xffff0000, v206
	v_pk_add_f32 v[68:69], v[68:69], 1.0 op_sel_hi:[1,0]
	v_pk_add_f32 v[70:71], v[70:71], 1.0 op_sel_hi:[1,0]
	v_lshlrev_b32_e32 v167, 16, v207
	v_and_b32_e32 v207, 0xffff0000, v207
	v_div_scale_f32 v140, s[6:7], v68, v68, v158
	v_div_scale_f32 v141, s[6:7], v69, v69, v206
	v_rcp_f32_e32 v144, v140
	v_rcp_f32_e32 v145, v141
	v_div_scale_f32 v142, vcc, v158, v68, v158
	v_div_scale_f32 v143, s[6:7], v206, v69, v206
	v_fma_f32 v146, -v140, v144, 1.0
	v_fma_f32 v147, -v141, v145, 1.0
	v_fmac_f32_e32 v144, v146, v144
	v_fmac_f32_e32 v145, v147, v145
	v_mul_f32_e32 v148, v142, v144
	v_mul_f32_e32 v149, v143, v145
	v_fma_f32 v146, -v140, v148, v142
	v_fma_f32 v147, -v141, v149, v143
	v_fmac_f32_e32 v148, v146, v144
	v_fmac_f32_e32 v149, v147, v145
	v_fma_f32 v146, -v140, v148, v142
	v_fma_f32 v147, -v141, v149, v143
	v_div_fmas_f32 v146, v146, v144, v148
	s_mov_b64 vcc, s[6:7]
	v_div_fixup_f32 v68, v146, v68, v158
	s_nop 1
	v_div_fmas_f32 v147, v147, v145, v149
	v_div_fixup_f32 v69, v147, v69, v206
	v_div_scale_f32 v140, s[6:7], v70, v70, v167
	v_div_scale_f32 v141, s[6:7], v71, v71, v207
	v_rcp_f32_e32 v144, v140
	v_rcp_f32_e32 v145, v141
	v_div_scale_f32 v142, vcc, v167, v70, v167
	v_div_scale_f32 v143, s[6:7], v207, v71, v207
	v_fma_f32 v146, -v140, v144, 1.0
	v_fma_f32 v147, -v141, v145, 1.0
	v_fmac_f32_e32 v144, v146, v144
	v_fmac_f32_e32 v145, v147, v145
	v_mul_f32_e32 v148, v142, v144
	v_mul_f32_e32 v149, v143, v145
	v_fma_f32 v146, -v140, v148, v142
	v_fma_f32 v147, -v141, v149, v143
	v_fmac_f32_e32 v148, v146, v144
	v_fmac_f32_e32 v149, v147, v145
	v_fma_f32 v146, -v140, v148, v142
	v_fma_f32 v147, -v141, v149, v143
	v_div_fmas_f32 v146, v146, v144, v148
	s_mov_b64 vcc, s[6:7]
	v_div_fixup_f32 v70, v146, v70, v167
	s_nop 1
	v_div_fmas_f32 v147, v147, v145, v149
	v_div_fixup_f32 v71, v147, v71, v207
	v_cvt_pk_bf16_f32 v68, v68, v69
	v_cvt_pk_bf16_f32 v69, v70, v71
	s_waitcnt vmcnt(6)
	v_mul_f32_e32 v64, 0xbfb8aa3b, v64
	v_mul_f32_e32 v65, 0xbfb8aa3b, v65
	v_mul_f32_e32 v66, 0xbfb8aa3b, v66
	v_mul_f32_e32 v67, 0xbfb8aa3b, v67
	v_exp_f32_e32 v64, v64
	v_exp_f32_e32 v65, v65
	v_exp_f32_e32 v66, v66
	v_exp_f32_e32 v67, v67
	v_lshlrev_b32_e32 v158, 16, v208
	v_and_b32_e32 v208, 0xffff0000, v208
	v_pk_add_f32 v[64:65], v[64:65], 1.0 op_sel_hi:[1,0]
	v_pk_add_f32 v[66:67], v[66:67], 1.0 op_sel_hi:[1,0]
	v_lshlrev_b32_e32 v167, 16, v209
	v_and_b32_e32 v209, 0xffff0000, v209
	v_div_scale_f32 v140, s[6:7], v64, v64, v158
	v_div_scale_f32 v141, s[6:7], v65, v65, v208
	v_rcp_f32_e32 v144, v140
	v_rcp_f32_e32 v145, v141
	v_div_scale_f32 v142, vcc, v158, v64, v158
	v_div_scale_f32 v143, s[6:7], v208, v65, v208
	v_fma_f32 v146, -v140, v144, 1.0
	v_fma_f32 v147, -v141, v145, 1.0
	v_fmac_f32_e32 v144, v146, v144
	v_fmac_f32_e32 v145, v147, v145
	v_mul_f32_e32 v148, v142, v144
	v_mul_f32_e32 v149, v143, v145
	v_fma_f32 v146, -v140, v148, v142
	v_fma_f32 v147, -v141, v149, v143
	v_fmac_f32_e32 v148, v146, v144
	v_fmac_f32_e32 v149, v147, v145
	v_fma_f32 v146, -v140, v148, v142
	v_fma_f32 v147, -v141, v149, v143
	v_div_fmas_f32 v146, v146, v144, v148
	s_mov_b64 vcc, s[6:7]
	v_div_fixup_f32 v64, v146, v64, v158
	s_nop 1
	v_div_fmas_f32 v147, v147, v145, v149
	v_div_fixup_f32 v65, v147, v65, v208
	v_div_scale_f32 v140, s[6:7], v66, v66, v167
	v_div_scale_f32 v141, s[6:7], v67, v67, v209
	v_rcp_f32_e32 v144, v140
	v_rcp_f32_e32 v145, v141
	v_div_scale_f32 v142, vcc, v167, v66, v167
	v_div_scale_f32 v143, s[6:7], v209, v67, v209
	v_fma_f32 v146, -v140, v144, 1.0
	v_fma_f32 v147, -v141, v145, 1.0
	v_fmac_f32_e32 v144, v146, v144
	v_fmac_f32_e32 v145, v147, v145
	v_mul_f32_e32 v148, v142, v144
	v_mul_f32_e32 v149, v143, v145
	v_fma_f32 v146, -v140, v148, v142
	v_fma_f32 v147, -v141, v149, v143
	v_fmac_f32_e32 v148, v146, v144
	v_fmac_f32_e32 v149, v147, v145
	v_fma_f32 v146, -v140, v148, v142
	v_fma_f32 v147, -v141, v149, v143
	v_div_fmas_f32 v146, v146, v144, v148
	s_mov_b64 vcc, s[6:7]
	v_div_fixup_f32 v66, v146, v66, v167
	s_nop 1
	v_div_fmas_f32 v147, v147, v145, v149
	v_div_fixup_f32 v67, v147, v67, v209
	v_cvt_pk_bf16_f32 v64, v64, v65
	v_cvt_pk_bf16_f32 v65, v66, v67
	v_cndmask_b32_e64 v70, v68, v64, s[8:9]
	v_cndmask_b32_e64 v71, v69, v65, s[8:9]
	v_cndmask_b32_e64 v66, v64, v68, s[8:9]
	v_cndmask_b32_e64 v67, v65, v69, s[8:9]
	ds_permute_b32 v68, v159, v70
	ds_permute_b32 v69, v159, v71
	ds_permute_b32 v64, v166, v66
	ds_permute_b32 v65, v166, v67
	s_waitcnt lgkmcnt(4)
	v_cndmask_b32_e64 v102, v96, v100, s[10:11]
	v_cndmask_b32_e64 v103, v97, v101, s[10:11]
	v_cndmask_b32_e64 v100, v100, v96, s[10:11]
	v_cndmask_b32_e64 v101, v101, v97, s[10:11]
	v_add_u32_e32 v169, 0x18000, v168
	global_store_dwordx4 v169, v[100:103], s[12:13]
	s_waitcnt lgkmcnt(0)
	v_cndmask_b32_e64 v70, v64, v68, s[10:11]
	v_cndmask_b32_e64 v71, v65, v69, s[10:11]
	v_cndmask_b32_e64 v68, v68, v64, s[10:11]
	v_cndmask_b32_e64 v69, v69, v65, s[10:11]
	v_add_u32_e32 v169, 0x18100, v168
	global_store_dwordx4 v169, v[68:71], s[12:13]
	s_branch .Lglu_end
.Lglu_r1:
	s_lshl_b32 s8, s6, 8
	v_add_u32_e32 v158, s8, v160
	v_lshl_or_b32 v159, s7, 8, v162
	v_lshlrev_b32_e32 v166, 10, v158
	v_lshl_add_u32 v166, v159, 1, v166
	v_add_u32_e32 v167, 0x20000, v166
	global_load_dwordx2 v[210:211], v167, s[14:15]
	global_load_dwordx2 v[212:213], v167, s[14:15] offset:32
	global_load_dwordx2 v[214:215], v167, s[14:15] offset:256
	global_load_dwordx2 v[216:217], v167, s[14:15] offset:288
	v_add_u32_e32 v167, 0x24000, v166
	global_load_dwordx2 v[218:219], v167, s[14:15]
	global_load_dwordx2 v[220:221], v167, s[14:15] offset:32
	global_load_dwordx2 v[222:223], v167, s[14:15] offset:256
	global_load_dwordx2 v[224:225], v167, s[14:15] offset:288
	v_add_u32_e32 v167, 0x28000, v166
	global_load_dwordx2 v[226:227], v167, s[14:15]
	global_load_dwordx2 v[228:229], v167, s[14:15] offset:32
	global_load_dwordx2 v[230:231], v167, s[14:15] offset:256
	global_load_dwordx2 v[232:233], v167, s[14:15] offset:288
	v_add_u32_e32 v167, 0x2c000, v166
	global_load_dwordx2 v[150:151], v167, s[14:15]
	global_load_dwordx2 v[152:153], v167, s[14:15] offset:32
	global_load_dwordx2 v[154:155], v167, s[14:15] offset:256
	global_load_dwordx2 v[156:157], v167, s[14:15] offset:288
	v_lshlrev_b32_e32 v168, 11, v158
	v_lshl_add_u32 v168, v159, 1, v168
	v_bfe_u32 v169, v162, 2, 2
	v_lshl_add_u32 v168, v169, 3, v168
	v_add_u32_e32 v168, 0xc99c400, v168
	v_and_b32_e32 v158, 15, v160
	v_and_b32_e32 v159, 1, v169
	v_lshrrev_b32_e32 v166, 1, v169
	v_lshl_or_b32 v159, v159, 1, v166
	v_xor_b32_e32 v166, 2, v159
	v_lshl_add_u32 v159, v159, 4, v158
	v_lshl_add_u32 v166, v166, 4, v158
	v_lshlrev_b32_e32 v159, 2, v159
	v_lshlrev_b32_e32 v166, 2, v166
	v_and_b32_e32 v167, 1, v169
	v_cmp_eq_u32_e64 s[8:9], 1, v167
	v_cmp_lt_u32_e64 s[10:11], 1, v169
	s_waitcnt vmcnt(15)
	v_mul_f32_e32 v60, 0xbfb8aa3b, v60
	v_mul_f32_e32 v61, 0xbfb8aa3b, v61
	v_mul_f32_e32 v62, 0xbfb8aa3b, v62
	v_mul_f32_e32 v63, 0xbfb8aa3b, v63
	v_exp_f32_e32 v60, v60
	v_exp_f32_e32 v61, v61
	v_exp_f32_e32 v62, v62
	v_exp_f32_e32 v63, v63
	v_lshlrev_b32_e32 v158, 16, v210
	v_and_b32_e32 v210, 0xffff0000, v210
	v_pk_add_f32 v[60:61], v[60:61], 1.0 op_sel_hi:[1,0]
	v_pk_add_f32 v[62:63], v[62:63], 1.0 op_sel_hi:[1,0]
	v_lshlrev_b32_e32 v167, 16, v211
	v_and_b32_e32 v211, 0xffff0000, v211
	v_div_scale_f32 v140, s[6:7], v60, v60, v158
	v_div_scale_f32 v141, s[6:7], v61, v61, v210
	v_rcp_f32_e32 v144, v140
	v_rcp_f32_e32 v145, v141
	v_div_scale_f32 v142, vcc, v158, v60, v158
	v_div_scale_f32 v143, s[6:7], v210, v61, v210
	v_fma_f32 v146, -v140, v144, 1.0
	v_fma_f32 v147, -v141, v145, 1.0
	v_fmac_f32_e32 v144, v146, v144
	v_fmac_f32_e32 v145, v147, v145
	v_mul_f32_e32 v148, v142, v144
	v_mul_f32_e32 v149, v143, v145
	v_fma_f32 v146, -v140, v148, v142
	v_fma_f32 v147, -v141, v149, v143
	v_fmac_f32_e32 v148, v146, v144
	v_fmac_f32_e32 v149, v147, v145
	v_fma_f32 v146, -v140, v148, v142
	v_fma_f32 v147, -v141, v149, v143
	v_div_fmas_f32 v146, v146, v144, v148
	s_mov_b64 vcc, s[6:7]
	v_div_fixup_f32 v60, v146, v60, v158
	s_nop 1
	v_div_fmas_f32 v147, v147, v145, v149
	v_div_fixup_f32 v61, v147, v61, v210
	v_div_scale_f32 v140, s[6:7], v62, v62, v167
	v_div_scale_f32 v141, s[6:7], v63, v63, v211
	v_rcp_f32_e32 v144, v140
	v_rcp_f32_e32 v145, v141
	v_div_scale_f32 v142, vcc, v167, v62, v167
	v_div_scale_f32 v143, s[6:7], v211, v63, v211
	v_fma_f32 v146, -v140, v144, 1.0
	v_fma_f32 v147, -v141, v145, 1.0
	v_fmac_f32_e32 v144, v146, v144
	v_fmac_f32_e32 v145, v147, v145
	v_mul_f32_e32 v148, v142, v144
	v_mul_f32_e32 v149, v143, v145
	v_fma_f32 v146, -v140, v148, v142
	v_fma_f32 v147, -v141, v149, v143
	v_fmac_f32_e32 v148, v146, v144
	v_fmac_f32_e32 v149, v147, v145
	v_fma_f32 v146, -v140, v148, v142
	v_fma_f32 v147, -v141, v149, v143
	v_div_fmas_f32 v146, v146, v144, v148
	s_mov_b64 vcc, s[6:7]
	v_div_fixup_f32 v62, v146, v62, v167
	s_nop 1
	v_div_fmas_f32 v147, v147, v145, v149
	v_div_fixup_f32 v63, v147, v63, v211
	v_cvt_pk_bf16_f32 v60, v60, v61
	v_cvt_pk_bf16_f32 v61, v62, v63
	s_waitcnt vmcnt(14)
	v_mul_f32_e32 v56, 0xbfb8aa3b, v56
	v_mul_f32_e32 v57, 0xbfb8aa3b, v57
	v_mul_f32_e32 v58, 0xbfb8aa3b, v58
	v_mul_f32_e32 v59, 0xbfb8aa3b, v59
	v_exp_f32_e32 v56, v56
	v_exp_f32_e32 v57, v57
	v_exp_f32_e32 v58, v58
	v_exp_f32_e32 v59, v59
	v_lshlrev_b32_e32 v158, 16, v212
	v_and_b32_e32 v212, 0xffff0000, v212
	v_pk_add_f32 v[56:57], v[56:57], 1.0 op_sel_hi:[1,0]
	v_pk_add_f32 v[58:59], v[58:59], 1.0 op_sel_hi:[1,0]
	v_lshlrev_b32_e32 v167, 16, v213
	v_and_b32_e32 v213, 0xffff0000, v213
	v_div_scale_f32 v140, s[6:7], v56, v56, v158
	v_div_scale_f32 v141, s[6:7], v57, v57, v212
	v_rcp_f32_e32 v144, v140
	v_rcp_f32_e32 v145, v141
	v_div_scale_f32 v142, vcc, v158, v56, v158
	v_div_scale_f32 v143, s[6:7], v212, v57, v212
	v_fma_f32 v146, -v140, v144, 1.0
	v_fma_f32 v147, -v141, v145, 1.0
	v_fmac_f32_e32 v144, v146, v144
	v_fmac_f32_e32 v145, v147, v145
	v_mul_f32_e32 v148, v142, v144
	v_mul_f32_e32 v149, v143, v145
	v_fma_f32 v146, -v140, v148, v142
	v_fma_f32 v147, -v141, v149, v143
	v_fmac_f32_e32 v148, v146, v144
	v_fmac_f32_e32 v149, v147, v145
	v_fma_f32 v146, -v140, v148, v142
	v_fma_f32 v147, -v141, v149, v143
	v_div_fmas_f32 v146, v146, v144, v148
	s_mov_b64 vcc, s[6:7]
	v_div_fixup_f32 v56, v146, v56, v158
	s_nop 1
	v_div_fmas_f32 v147, v147, v145, v149
	v_div_fixup_f32 v57, v147, v57, v212
	v_div_scale_f32 v140, s[6:7], v58, v58, v167
	v_div_scale_f32 v141, s[6:7], v59, v59, v213
	v_rcp_f32_e32 v144, v140
	v_rcp_f32_e32 v145, v141
	v_div_scale_f32 v142, vcc, v167, v58, v167
	v_div_scale_f32 v143, s[6:7], v213, v59, v213
	v_fma_f32 v146, -v140, v144, 1.0
	v_fma_f32 v147, -v141, v145, 1.0
	v_fmac_f32_e32 v144, v146, v144
	v_fmac_f32_e32 v145, v147, v145
	v_mul_f32_e32 v148, v142, v144
	v_mul_f32_e32 v149, v143, v145
	v_fma_f32 v146, -v140, v148, v142
	v_fma_f32 v147, -v141, v149, v143
	v_fmac_f32_e32 v148, v146, v144
	v_fmac_f32_e32 v149, v147, v145
	v_fma_f32 v146, -v140, v148, v142
	v_fma_f32 v147, -v141, v149, v143
	v_div_fmas_f32 v146, v146, v144, v148
	s_mov_b64 vcc, s[6:7]
	v_div_fixup_f32 v58, v146, v58, v167
	s_nop 1
	v_div_fmas_f32 v147, v147, v145, v149
	v_div_fixup_f32 v59, v147, v59, v213
	v_cvt_pk_bf16_f32 v56, v56, v57
	v_cvt_pk_bf16_f32 v57, v58, v59
	v_cndmask_b32_e64 v62, v60, v56, s[8:9]
	v_cndmask_b32_e64 v63, v61, v57, s[8:9]
	v_cndmask_b32_e64 v58, v56, v60, s[8:9]
	v_cndmask_b32_e64 v59, v57, v61, s[8:9]
	ds_permute_b32 v60, v159, v62
	ds_permute_b32 v61, v159, v63
	ds_permute_b32 v56, v166, v58
	ds_permute_b32 v57, v166, v59
	s_waitcnt vmcnt(13)
	v_mul_f32_e32 v28, 0xbfb8aa3b, v28
	v_mul_f32_e32 v29, 0xbfb8aa3b, v29
	v_mul_f32_e32 v30, 0xbfb8aa3b, v30
	v_mul_f32_e32 v31, 0xbfb8aa3b, v31
	v_exp_f32_e32 v28, v28
	v_exp_f32_e32 v29, v29
	v_exp_f32_e32 v30, v30
	v_exp_f32_e32 v31, v31
	v_lshlrev_b32_e32 v158, 16, v214
	v_and_b32_e32 v214, 0xffff0000, v214
	v_pk_add_f32 v[28:29], v[28:29], 1.0 op_sel_hi:[1,0]
	v_pk_add_f32 v[30:31], v[30:31], 1.0 op_sel_hi:[1,0]
	v_lshlrev_b32_e32 v167, 16, v215
	v_and_b32_e32 v215, 0xffff0000, v215
	v_div_scale_f32 v140, s[6:7], v28, v28, v158
	v_div_scale_f32 v141, s[6:7], v29, v29, v214
	v_rcp_f32_e32 v144, v140
	v_rcp_f32_e32 v145, v141
	v_div_scale_f32 v142, vcc, v158, v28, v158
	v_div_scale_f32 v143, s[6:7], v214, v29, v214
	v_fma_f32 v146, -v140, v144, 1.0
	v_fma_f32 v147, -v141, v145, 1.0
	v_fmac_f32_e32 v144, v146, v144
	v_fmac_f32_e32 v145, v147, v145
	v_mul_f32_e32 v148, v142, v144
	v_mul_f32_e32 v149, v143, v145
	v_fma_f32 v146, -v140, v148, v142
	v_fma_f32 v147, -v141, v149, v143
	v_fmac_f32_e32 v148, v146, v144
	v_fmac_f32_e32 v149, v147, v145
	v_fma_f32 v146, -v140, v148, v142
	v_fma_f32 v147, -v141, v149, v143
	v_div_fmas_f32 v146, v146, v144, v148
	s_mov_b64 vcc, s[6:7]
	v_div_fixup_f32 v28, v146, v28, v158
	s_nop 1
	v_div_fmas_f32 v147, v147, v145, v149
	v_div_fixup_f32 v29, v147, v29, v214
	v_div_scale_f32 v140, s[6:7], v30, v30, v167
	v_div_scale_f32 v141, s[6:7], v31, v31, v215
	v_rcp_f32_e32 v144, v140
	v_rcp_f32_e32 v145, v141
	v_div_scale_f32 v142, vcc, v167, v30, v167
	v_div_scale_f32 v143, s[6:7], v215, v31, v215
	v_fma_f32 v146, -v140, v144, 1.0
	v_fma_f32 v147, -v141, v145, 1.0
	v_fmac_f32_e32 v144, v146, v144
	v_fmac_f32_e32 v145, v147, v145
	v_mul_f32_e32 v148, v142, v144
	v_mul_f32_e32 v149, v143, v145
	v_fma_f32 v146, -v140, v148, v142
	v_fma_f32 v147, -v141, v149, v143
	v_fmac_f32_e32 v148, v146, v144
	v_fmac_f32_e32 v149, v147, v145
	v_fma_f32 v146, -v140, v148, v142
	v_fma_f32 v147, -v141, v149, v143
	v_div_fmas_f32 v146, v146, v144, v148
	s_mov_b64 vcc, s[6:7]
	v_div_fixup_f32 v30, v146, v30, v167
	s_nop 1
	v_div_fmas_f32 v147, v147, v145, v149
	v_div_fixup_f32 v31, v147, v31, v215
	v_cvt_pk_bf16_f32 v28, v28, v29
	v_cvt_pk_bf16_f32 v29, v30, v31
	s_waitcnt vmcnt(12)
	v_mul_f32_e32 v24, 0xbfb8aa3b, v24
	v_mul_f32_e32 v25, 0xbfb8aa3b, v25
	v_mul_f32_e32 v26, 0xbfb8aa3b, v26
	v_mul_f32_e32 v27, 0xbfb8aa3b, v27
	v_exp_f32_e32 v24, v24
	v_exp_f32_e32 v25, v25
	v_exp_f32_e32 v26, v26
	v_exp_f32_e32 v27, v27
	v_lshlrev_b32_e32 v158, 16, v216
	v_and_b32_e32 v216, 0xffff0000, v216
	v_pk_add_f32 v[24:25], v[24:25], 1.0 op_sel_hi:[1,0]
	v_pk_add_f32 v[26:27], v[26:27], 1.0 op_sel_hi:[1,0]
	v_lshlrev_b32_e32 v167, 16, v217
	v_and_b32_e32 v217, 0xffff0000, v217
	v_div_scale_f32 v140, s[6:7], v24, v24, v158
	v_div_scale_f32 v141, s[6:7], v25, v25, v216
	v_rcp_f32_e32 v144, v140
	v_rcp_f32_e32 v145, v141
	v_div_scale_f32 v142, vcc, v158, v24, v158
	v_div_scale_f32 v143, s[6:7], v216, v25, v216
	v_fma_f32 v146, -v140, v144, 1.0
	v_fma_f32 v147, -v141, v145, 1.0
	v_fmac_f32_e32 v144, v146, v144
	v_fmac_f32_e32 v145, v147, v145
	v_mul_f32_e32 v148, v142, v144
	v_mul_f32_e32 v149, v143, v145
	v_fma_f32 v146, -v140, v148, v142
	v_fma_f32 v147, -v141, v149, v143
	v_fmac_f32_e32 v148, v146, v144
	v_fmac_f32_e32 v149, v147, v145
	v_fma_f32 v146, -v140, v148, v142
	v_fma_f32 v147, -v141, v149, v143
	v_div_fmas_f32 v146, v146, v144, v148
	s_mov_b64 vcc, s[6:7]
	v_div_fixup_f32 v24, v146, v24, v158
	s_nop 1
	v_div_fmas_f32 v147, v147, v145, v149
	v_div_fixup_f32 v25, v147, v25, v216
	v_div_scale_f32 v140, s[6:7], v26, v26, v167
	v_div_scale_f32 v141, s[6:7], v27, v27, v217
	v_rcp_f32_e32 v144, v140
	v_rcp_f32_e32 v145, v141
	v_div_scale_f32 v142, vcc, v167, v26, v167
	v_div_scale_f32 v143, s[6:7], v217, v27, v217
	v_fma_f32 v146, -v140, v144, 1.0
	v_fma_f32 v147, -v141, v145, 1.0
	v_fmac_f32_e32 v144, v146, v144
	v_fmac_f32_e32 v145, v147, v145
	v_mul_f32_e32 v148, v142, v144
	v_mul_f32_e32 v149, v143, v145
	v_fma_f32 v146, -v140, v148, v142
	v_fma_f32 v147, -v141, v149, v143
	v_fmac_f32_e32 v148, v146, v144
	v_fmac_f32_e32 v149, v147, v145
	v_fma_f32 v146, -v140, v148, v142
	v_fma_f32 v147, -v141, v149, v143
	v_div_fmas_f32 v146, v146, v144, v148
	s_mov_b64 vcc, s[6:7]
	v_div_fixup_f32 v26, v146, v26, v167
	s_nop 1
	v_div_fmas_f32 v147, v147, v145, v149
	v_div_fixup_f32 v27, v147, v27, v217
	v_cvt_pk_bf16_f32 v24, v24, v25
	v_cvt_pk_bf16_f32 v25, v26, v27
	v_cndmask_b32_e64 v30, v28, v24, s[8:9]
	v_cndmask_b32_e64 v31, v29, v25, s[8:9]
	v_cndmask_b32_e64 v26, v24, v28, s[8:9]
	v_cndmask_b32_e64 v27, v25, v29, s[8:9]
	ds_permute_b32 v28, v159, v30
	ds_permute_b32 v29, v159, v31
	ds_permute_b32 v24, v166, v26
	ds_permute_b32 v25, v166, v27
	s_waitcnt lgkmcnt(4)
	v_cndmask_b32_e64 v62, v56, v60, s[10:11]
	v_cndmask_b32_e64 v63, v57, v61, s[10:11]
	v_cndmask_b32_e64 v60, v60, v56, s[10:11]
	v_cndmask_b32_e64 v61, v61, v57, s[10:11]
	v_add_u32_e32 v169, 0x40000, v168
	global_store_dwordx4 v169, v[60:63], s[12:13]
	s_waitcnt vmcnt(12)
	v_mul_f32_e32 v52, 0xbfb8aa3b, v52
	v_mul_f32_e32 v53, 0xbfb8aa3b, v53
	v_mul_f32_e32 v54, 0xbfb8aa3b, v54
	v_mul_f32_e32 v55, 0xbfb8aa3b, v55
	v_exp_f32_e32 v52, v52
	v_exp_f32_e32 v53, v53
	v_exp_f32_e32 v54, v54
	v_exp_f32_e32 v55, v55
	v_lshlrev_b32_e32 v158, 16, v218
	v_and_b32_e32 v218, 0xffff0000, v218
	v_pk_add_f32 v[52:53], v[52:53], 1.0 op_sel_hi:[1,0]
	v_pk_add_f32 v[54:55], v[54:55], 1.0 op_sel_hi:[1,0]
	v_lshlrev_b32_e32 v167, 16, v219
	v_and_b32_e32 v219, 0xffff0000, v219
	v_div_scale_f32 v140, s[6:7], v52, v52, v158
	v_div_scale_f32 v141, s[6:7], v53, v53, v218
	v_rcp_f32_e32 v144, v140
	v_rcp_f32_e32 v145, v141
	v_div_scale_f32 v142, vcc, v158, v52, v158
	v_div_scale_f32 v143, s[6:7], v218, v53, v218
	v_fma_f32 v146, -v140, v144, 1.0
	v_fma_f32 v147, -v141, v145, 1.0
	v_fmac_f32_e32 v144, v146, v144
	v_fmac_f32_e32 v145, v147, v145
	v_mul_f32_e32 v148, v142, v144
	v_mul_f32_e32 v149, v143, v145
	v_fma_f32 v146, -v140, v148, v142
	v_fma_f32 v147, -v141, v149, v143
	v_fmac_f32_e32 v148, v146, v144
	v_fmac_f32_e32 v149, v147, v145
	v_fma_f32 v146, -v140, v148, v142
	v_fma_f32 v147, -v141, v149, v143
	v_div_fmas_f32 v146, v146, v144, v148
	s_mov_b64 vcc, s[6:7]
	v_div_fixup_f32 v52, v146, v52, v158
	s_nop 1
	v_div_fmas_f32 v147, v147, v145, v149
	v_div_fixup_f32 v53, v147, v53, v218
	v_div_scale_f32 v140, s[6:7], v54, v54, v167
	v_div_scale_f32 v141, s[6:7], v55, v55, v219
	v_rcp_f32_e32 v144, v140
	v_rcp_f32_e32 v145, v141
	v_div_scale_f32 v142, vcc, v167, v54, v167
	v_div_scale_f32 v143, s[6:7], v219, v55, v219
	v_fma_f32 v146, -v140, v144, 1.0
	v_fma_f32 v147, -v141, v145, 1.0
	v_fmac_f32_e32 v144, v146, v144
	v_fmac_f32_e32 v145, v147, v145
	v_mul_f32_e32 v148, v142, v144
	v_mul_f32_e32 v149, v143, v145
	v_fma_f32 v146, -v140, v148, v142
	v_fma_f32 v147, -v141, v149, v143
	v_fmac_f32_e32 v148, v146, v144
	v_fmac_f32_e32 v149, v147, v145
	v_fma_f32 v146, -v140, v148, v142
	v_fma_f32 v147, -v141, v149, v143
	v_div_fmas_f32 v146, v146, v144, v148
	s_mov_b64 vcc, s[6:7]
	v_div_fixup_f32 v54, v146, v54, v167
	s_nop 1
	v_div_fmas_f32 v147, v147, v145, v149
	v_div_fixup_f32 v55, v147, v55, v219
	v_cvt_pk_bf16_f32 v52, v52, v53
	v_cvt_pk_bf16_f32 v53, v54, v55
	s_waitcnt vmcnt(11)
	v_mul_f32_e32 v48, 0xbfb8aa3b, v48
	v_mul_f32_e32 v49, 0xbfb8aa3b, v49
	v_mul_f32_e32 v50, 0xbfb8aa3b, v50
	v_mul_f32_e32 v51, 0xbfb8aa3b, v51
	v_exp_f32_e32 v48, v48
	v_exp_f32_e32 v49, v49
	v_exp_f32_e32 v50, v50
	v_exp_f32_e32 v51, v51
	v_lshlrev_b32_e32 v158, 16, v220
	v_and_b32_e32 v220, 0xffff0000, v220
	v_pk_add_f32 v[48:49], v[48:49], 1.0 op_sel_hi:[1,0]
	v_pk_add_f32 v[50:51], v[50:51], 1.0 op_sel_hi:[1,0]
	v_lshlrev_b32_e32 v167, 16, v221
	v_and_b32_e32 v221, 0xffff0000, v221
	v_div_scale_f32 v140, s[6:7], v48, v48, v158
	v_div_scale_f32 v141, s[6:7], v49, v49, v220
	v_rcp_f32_e32 v144, v140
	v_rcp_f32_e32 v145, v141
	v_div_scale_f32 v142, vcc, v158, v48, v158
	v_div_scale_f32 v143, s[6:7], v220, v49, v220
	v_fma_f32 v146, -v140, v144, 1.0
	v_fma_f32 v147, -v141, v145, 1.0
	v_fmac_f32_e32 v144, v146, v144
	v_fmac_f32_e32 v145, v147, v145
	v_mul_f32_e32 v148, v142, v144
	v_mul_f32_e32 v149, v143, v145
	v_fma_f32 v146, -v140, v148, v142
	v_fma_f32 v147, -v141, v149, v143
	v_fmac_f32_e32 v148, v146, v144
	v_fmac_f32_e32 v149, v147, v145
	v_fma_f32 v146, -v140, v148, v142
	v_fma_f32 v147, -v141, v149, v143
	v_div_fmas_f32 v146, v146, v144, v148
	s_mov_b64 vcc, s[6:7]
	v_div_fixup_f32 v48, v146, v48, v158
	s_nop 1
	v_div_fmas_f32 v147, v147, v145, v149
	v_div_fixup_f32 v49, v147, v49, v220
	v_div_scale_f32 v140, s[6:7], v50, v50, v167
	v_div_scale_f32 v141, s[6:7], v51, v51, v221
	v_rcp_f32_e32 v144, v140
	v_rcp_f32_e32 v145, v141
	v_div_scale_f32 v142, vcc, v167, v50, v167
	v_div_scale_f32 v143, s[6:7], v221, v51, v221
	v_fma_f32 v146, -v140, v144, 1.0
	v_fma_f32 v147, -v141, v145, 1.0
	v_fmac_f32_e32 v144, v146, v144
	v_fmac_f32_e32 v145, v147, v145
	v_mul_f32_e32 v148, v142, v144
	v_mul_f32_e32 v149, v143, v145
	v_fma_f32 v146, -v140, v148, v142
	v_fma_f32 v147, -v141, v149, v143
	v_fmac_f32_e32 v148, v146, v144
	v_fmac_f32_e32 v149, v147, v145
	v_fma_f32 v146, -v140, v148, v142
	v_fma_f32 v147, -v141, v149, v143
	v_div_fmas_f32 v146, v146, v144, v148
	s_mov_b64 vcc, s[6:7]
	v_div_fixup_f32 v50, v146, v50, v167
	s_nop 1
	v_div_fmas_f32 v147, v147, v145, v149
	v_div_fixup_f32 v51, v147, v51, v221
	v_cvt_pk_bf16_f32 v48, v48, v49
	v_cvt_pk_bf16_f32 v49, v50, v51
	v_cndmask_b32_e64 v54, v52, v48, s[8:9]
	v_cndmask_b32_e64 v55, v53, v49, s[8:9]
	v_cndmask_b32_e64 v50, v48, v52, s[8:9]
	v_cndmask_b32_e64 v51, v49, v53, s[8:9]
	ds_permute_b32 v52, v159, v54
	ds_permute_b32 v53, v159, v55
	ds_permute_b32 v48, v166, v50
	ds_permute_b32 v49, v166, v51
	s_waitcnt lgkmcnt(4)
	v_cndmask_b32_e64 v30, v24, v28, s[10:11]
	v_cndmask_b32_e64 v31, v25, v29, s[10:11]
	v_cndmask_b32_e64 v28, v28, v24, s[10:11]
	v_cndmask_b32_e64 v29, v29, v25, s[10:11]
	v_add_u32_e32 v169, 0x40100, v168
	global_store_dwordx4 v169, v[28:31], s[12:13]
	s_waitcnt vmcnt(11)
	v_mul_f32_e32 v20, 0xbfb8aa3b, v20
	v_mul_f32_e32 v21, 0xbfb8aa3b, v21
	v_mul_f32_e32 v22, 0xbfb8aa3b, v22
	v_mul_f32_e32 v23, 0xbfb8aa3b, v23
	v_exp_f32_e32 v20, v20
	v_exp_f32_e32 v21, v21
	v_exp_f32_e32 v22, v22
	v_exp_f32_e32 v23, v23
	v_lshlrev_b32_e32 v158, 16, v222
	v_and_b32_e32 v222, 0xffff0000, v222
	v_pk_add_f32 v[20:21], v[20:21], 1.0 op_sel_hi:[1,0]
	v_pk_add_f32 v[22:23], v[22:23], 1.0 op_sel_hi:[1,0]
	v_lshlrev_b32_e32 v167, 16, v223
	v_and_b32_e32 v223, 0xffff0000, v223
	v_div_scale_f32 v140, s[6:7], v20, v20, v158
	v_div_scale_f32 v141, s[6:7], v21, v21, v222
	v_rcp_f32_e32 v144, v140
	v_rcp_f32_e32 v145, v141
	v_div_scale_f32 v142, vcc, v158, v20, v158
	v_div_scale_f32 v143, s[6:7], v222, v21, v222
	v_fma_f32 v146, -v140, v144, 1.0
	v_fma_f32 v147, -v141, v145, 1.0
	v_fmac_f32_e32 v144, v146, v144
	v_fmac_f32_e32 v145, v147, v145
	v_mul_f32_e32 v148, v142, v144
	v_mul_f32_e32 v149, v143, v145
	v_fma_f32 v146, -v140, v148, v142
	v_fma_f32 v147, -v141, v149, v143
	v_fmac_f32_e32 v148, v146, v144
	v_fmac_f32_e32 v149, v147, v145
	v_fma_f32 v146, -v140, v148, v142
	v_fma_f32 v147, -v141, v149, v143
	v_div_fmas_f32 v146, v146, v144, v148
	s_mov_b64 vcc, s[6:7]
	v_div_fixup_f32 v20, v146, v20, v158
	s_nop 1
	v_div_fmas_f32 v147, v147, v145, v149
	v_div_fixup_f32 v21, v147, v21, v222
	v_div_scale_f32 v140, s[6:7], v22, v22, v167
	v_div_scale_f32 v141, s[6:7], v23, v23, v223
	v_rcp_f32_e32 v144, v140
	v_rcp_f32_e32 v145, v141
	v_div_scale_f32 v142, vcc, v167, v22, v167
	v_div_scale_f32 v143, s[6:7], v223, v23, v223
	v_fma_f32 v146, -v140, v144, 1.0
	v_fma_f32 v147, -v141, v145, 1.0
	v_fmac_f32_e32 v144, v146, v144
	v_fmac_f32_e32 v145, v147, v145
	v_mul_f32_e32 v148, v142, v144
	v_mul_f32_e32 v149, v143, v145
	v_fma_f32 v146, -v140, v148, v142
	v_fma_f32 v147, -v141, v149, v143
	v_fmac_f32_e32 v148, v146, v144
	v_fmac_f32_e32 v149, v147, v145
	v_fma_f32 v146, -v140, v148, v142
	v_fma_f32 v147, -v141, v149, v143
	v_div_fmas_f32 v146, v146, v144, v148
	s_mov_b64 vcc, s[6:7]
	v_div_fixup_f32 v22, v146, v22, v167
	s_nop 1
	v_div_fmas_f32 v147, v147, v145, v149
	v_div_fixup_f32 v23, v147, v23, v223
	v_cvt_pk_bf16_f32 v20, v20, v21
	v_cvt_pk_bf16_f32 v21, v22, v23
	s_waitcnt vmcnt(10)
	v_mul_f32_e32 v16, 0xbfb8aa3b, v16
	v_mul_f32_e32 v17, 0xbfb8aa3b, v17
	v_mul_f32_e32 v18, 0xbfb8aa3b, v18
	v_mul_f32_e32 v19, 0xbfb8aa3b, v19
	v_exp_f32_e32 v16, v16
	v_exp_f32_e32 v17, v17
	v_exp_f32_e32 v18, v18
	v_exp_f32_e32 v19, v19
	v_lshlrev_b32_e32 v158, 16, v224
	v_and_b32_e32 v224, 0xffff0000, v224
	v_pk_add_f32 v[16:17], v[16:17], 1.0 op_sel_hi:[1,0]
	v_pk_add_f32 v[18:19], v[18:19], 1.0 op_sel_hi:[1,0]
	v_lshlrev_b32_e32 v167, 16, v225
	v_and_b32_e32 v225, 0xffff0000, v225
	v_div_scale_f32 v140, s[6:7], v16, v16, v158
	v_div_scale_f32 v141, s[6:7], v17, v17, v224
	v_rcp_f32_e32 v144, v140
	v_rcp_f32_e32 v145, v141
	v_div_scale_f32 v142, vcc, v158, v16, v158
	v_div_scale_f32 v143, s[6:7], v224, v17, v224
	v_fma_f32 v146, -v140, v144, 1.0
	v_fma_f32 v147, -v141, v145, 1.0
	v_fmac_f32_e32 v144, v146, v144
	v_fmac_f32_e32 v145, v147, v145
	v_mul_f32_e32 v148, v142, v144
	v_mul_f32_e32 v149, v143, v145
	v_fma_f32 v146, -v140, v148, v142
	v_fma_f32 v147, -v141, v149, v143
	v_fmac_f32_e32 v148, v146, v144
	v_fmac_f32_e32 v149, v147, v145
	v_fma_f32 v146, -v140, v148, v142
	v_fma_f32 v147, -v141, v149, v143
	v_div_fmas_f32 v146, v146, v144, v148
	s_mov_b64 vcc, s[6:7]
	v_div_fixup_f32 v16, v146, v16, v158
	s_nop 1
	v_div_fmas_f32 v147, v147, v145, v149
	v_div_fixup_f32 v17, v147, v17, v224
	v_div_scale_f32 v140, s[6:7], v18, v18, v167
	v_div_scale_f32 v141, s[6:7], v19, v19, v225
	v_rcp_f32_e32 v144, v140
	v_rcp_f32_e32 v145, v141
	v_div_scale_f32 v142, vcc, v167, v18, v167
	v_div_scale_f32 v143, s[6:7], v225, v19, v225
	v_fma_f32 v146, -v140, v144, 1.0
	v_fma_f32 v147, -v141, v145, 1.0
	v_fmac_f32_e32 v144, v146, v144
	v_fmac_f32_e32 v145, v147, v145
	v_mul_f32_e32 v148, v142, v144
	v_mul_f32_e32 v149, v143, v145
	v_fma_f32 v146, -v140, v148, v142
	v_fma_f32 v147, -v141, v149, v143
	v_fmac_f32_e32 v148, v146, v144
	v_fmac_f32_e32 v149, v147, v145
	v_fma_f32 v146, -v140, v148, v142
	v_fma_f32 v147, -v141, v149, v143
	v_div_fmas_f32 v146, v146, v144, v148
	s_mov_b64 vcc, s[6:7]
	v_div_fixup_f32 v18, v146, v18, v167
	s_nop 1
	v_div_fmas_f32 v147, v147, v145, v149
	v_div_fixup_f32 v19, v147, v19, v225
	v_cvt_pk_bf16_f32 v16, v16, v17
	v_cvt_pk_bf16_f32 v17, v18, v19
	v_cndmask_b32_e64 v22, v20, v16, s[8:9]
	v_cndmask_b32_e64 v23, v21, v17, s[8:9]
	v_cndmask_b32_e64 v18, v16, v20, s[8:9]
	v_cndmask_b32_e64 v19, v17, v21, s[8:9]
	ds_permute_b32 v20, v159, v22
	ds_permute_b32 v21, v159, v23
	ds_permute_b32 v16, v166, v18
	ds_permute_b32 v17, v166, v19
	s_waitcnt lgkmcnt(4)
	v_cndmask_b32_e64 v54, v48, v52, s[10:11]
	v_cndmask_b32_e64 v55, v49, v53, s[10:11]
	v_cndmask_b32_e64 v52, v52, v48, s[10:11]
	v_cndmask_b32_e64 v53, v53, v49, s[10:11]
	v_add_u32_e32 v169, 0x48000, v168
	global_store_dwordx4 v169, v[52:55], s[12:13]
	s_waitcnt vmcnt(10)
	v_mul_f32_e32 v44, 0xbfb8aa3b, v44
	v_mul_f32_e32 v45, 0xbfb8aa3b, v45
	v_mul_f32_e32 v46, 0xbfb8aa3b, v46
	v_mul_f32_e32 v47, 0xbfb8aa3b, v47
	v_exp_f32_e32 v44, v44
	v_exp_f32_e32 v45, v45
	v_exp_f32_e32 v46, v46
	v_exp_f32_e32 v47, v47
	v_lshlrev_b32_e32 v158, 16, v226
	v_and_b32_e32 v226, 0xffff0000, v226
	v_pk_add_f32 v[44:45], v[44:45], 1.0 op_sel_hi:[1,0]
	v_pk_add_f32 v[46:47], v[46:47], 1.0 op_sel_hi:[1,0]
	v_lshlrev_b32_e32 v167, 16, v227
	v_and_b32_e32 v227, 0xffff0000, v227
	v_div_scale_f32 v140, s[6:7], v44, v44, v158
	v_div_scale_f32 v141, s[6:7], v45, v45, v226
	v_rcp_f32_e32 v144, v140
	v_rcp_f32_e32 v145, v141
	v_div_scale_f32 v142, vcc, v158, v44, v158
	v_div_scale_f32 v143, s[6:7], v226, v45, v226
	v_fma_f32 v146, -v140, v144, 1.0
	v_fma_f32 v147, -v141, v145, 1.0
	v_fmac_f32_e32 v144, v146, v144
	v_fmac_f32_e32 v145, v147, v145
	v_mul_f32_e32 v148, v142, v144
	v_mul_f32_e32 v149, v143, v145
	v_fma_f32 v146, -v140, v148, v142
	v_fma_f32 v147, -v141, v149, v143
	v_fmac_f32_e32 v148, v146, v144
	v_fmac_f32_e32 v149, v147, v145
	v_fma_f32 v146, -v140, v148, v142
	v_fma_f32 v147, -v141, v149, v143
	v_div_fmas_f32 v146, v146, v144, v148
	s_mov_b64 vcc, s[6:7]
	v_div_fixup_f32 v44, v146, v44, v158
	s_nop 1
	v_div_fmas_f32 v147, v147, v145, v149
	v_div_fixup_f32 v45, v147, v45, v226
	v_div_scale_f32 v140, s[6:7], v46, v46, v167
	v_div_scale_f32 v141, s[6:7], v47, v47, v227
	v_rcp_f32_e32 v144, v140
	v_rcp_f32_e32 v145, v141
	v_div_scale_f32 v142, vcc, v167, v46, v167
	v_div_scale_f32 v143, s[6:7], v227, v47, v227
	v_fma_f32 v146, -v140, v144, 1.0
	v_fma_f32 v147, -v141, v145, 1.0
	v_fmac_f32_e32 v144, v146, v144
	v_fmac_f32_e32 v145, v147, v145
	v_mul_f32_e32 v148, v142, v144
	v_mul_f32_e32 v149, v143, v145
	v_fma_f32 v146, -v140, v148, v142
	v_fma_f32 v147, -v141, v149, v143
	v_fmac_f32_e32 v148, v146, v144
	v_fmac_f32_e32 v149, v147, v145
	v_fma_f32 v146, -v140, v148, v142
	v_fma_f32 v147, -v141, v149, v143
	v_div_fmas_f32 v146, v146, v144, v148
	s_mov_b64 vcc, s[6:7]
	v_div_fixup_f32 v46, v146, v46, v167
	s_nop 1
	v_div_fmas_f32 v147, v147, v145, v149
	v_div_fixup_f32 v47, v147, v47, v227
	v_cvt_pk_bf16_f32 v44, v44, v45
	v_cvt_pk_bf16_f32 v45, v46, v47
	s_waitcnt vmcnt(9)
	v_mul_f32_e32 v40, 0xbfb8aa3b, v40
	v_mul_f32_e32 v41, 0xbfb8aa3b, v41
	v_mul_f32_e32 v42, 0xbfb8aa3b, v42
	v_mul_f32_e32 v43, 0xbfb8aa3b, v43
	v_exp_f32_e32 v40, v40
	v_exp_f32_e32 v41, v41
	v_exp_f32_e32 v42, v42
	v_exp_f32_e32 v43, v43
	v_lshlrev_b32_e32 v158, 16, v228
	v_and_b32_e32 v228, 0xffff0000, v228
	v_pk_add_f32 v[40:41], v[40:41], 1.0 op_sel_hi:[1,0]
	v_pk_add_f32 v[42:43], v[42:43], 1.0 op_sel_hi:[1,0]
	v_lshlrev_b32_e32 v167, 16, v229
	v_and_b32_e32 v229, 0xffff0000, v229
	v_div_scale_f32 v140, s[6:7], v40, v40, v158
	v_div_scale_f32 v141, s[6:7], v41, v41, v228
	v_rcp_f32_e32 v144, v140
	v_rcp_f32_e32 v145, v141
	v_div_scale_f32 v142, vcc, v158, v40, v158
	v_div_scale_f32 v143, s[6:7], v228, v41, v228
	v_fma_f32 v146, -v140, v144, 1.0
	v_fma_f32 v147, -v141, v145, 1.0
	v_fmac_f32_e32 v144, v146, v144
	v_fmac_f32_e32 v145, v147, v145
	v_mul_f32_e32 v148, v142, v144
	v_mul_f32_e32 v149, v143, v145
	v_fma_f32 v146, -v140, v148, v142
	v_fma_f32 v147, -v141, v149, v143
	v_fmac_f32_e32 v148, v146, v144
	v_fmac_f32_e32 v149, v147, v145
	v_fma_f32 v146, -v140, v148, v142
	v_fma_f32 v147, -v141, v149, v143
	v_div_fmas_f32 v146, v146, v144, v148
	s_mov_b64 vcc, s[6:7]
	v_div_fixup_f32 v40, v146, v40, v158
	s_nop 1
	v_div_fmas_f32 v147, v147, v145, v149
	v_div_fixup_f32 v41, v147, v41, v228
	v_div_scale_f32 v140, s[6:7], v42, v42, v167
	v_div_scale_f32 v141, s[6:7], v43, v43, v229
	v_rcp_f32_e32 v144, v140
	v_rcp_f32_e32 v145, v141
	v_div_scale_f32 v142, vcc, v167, v42, v167
	v_div_scale_f32 v143, s[6:7], v229, v43, v229
	v_fma_f32 v146, -v140, v144, 1.0
	v_fma_f32 v147, -v141, v145, 1.0
	v_fmac_f32_e32 v144, v146, v144
	v_fmac_f32_e32 v145, v147, v145
	v_mul_f32_e32 v148, v142, v144
	v_mul_f32_e32 v149, v143, v145
	v_fma_f32 v146, -v140, v148, v142
	v_fma_f32 v147, -v141, v149, v143
	v_fmac_f32_e32 v148, v146, v144
	v_fmac_f32_e32 v149, v147, v145
	v_fma_f32 v146, -v140, v148, v142
	v_fma_f32 v147, -v141, v149, v143
	v_div_fmas_f32 v146, v146, v144, v148
	s_mov_b64 vcc, s[6:7]
	v_div_fixup_f32 v42, v146, v42, v167
	s_nop 1
	v_div_fmas_f32 v147, v147, v145, v149
	v_div_fixup_f32 v43, v147, v43, v229
	v_cvt_pk_bf16_f32 v40, v40, v41
	v_cvt_pk_bf16_f32 v41, v42, v43
	v_cndmask_b32_e64 v46, v44, v40, s[8:9]
	v_cndmask_b32_e64 v47, v45, v41, s[8:9]
	v_cndmask_b32_e64 v42, v40, v44, s[8:9]
	v_cndmask_b32_e64 v43, v41, v45, s[8:9]
	ds_permute_b32 v44, v159, v46
	ds_permute_b32 v45, v159, v47
	ds_permute_b32 v40, v166, v42
	ds_permute_b32 v41, v166, v43
	s_waitcnt lgkmcnt(4)
	v_cndmask_b32_e64 v22, v16, v20, s[10:11]
	v_cndmask_b32_e64 v23, v17, v21, s[10:11]
	v_cndmask_b32_e64 v20, v20, v16, s[10:11]
	v_cndmask_b32_e64 v21, v21, v17, s[10:11]
	v_add_u32_e32 v169, 0x48100, v168
	global_store_dwordx4 v169, v[20:23], s[12:13]
	s_waitcnt vmcnt(9)
	v_mul_f32_e32 v12, 0xbfb8aa3b, v12
	v_mul_f32_e32 v13, 0xbfb8aa3b, v13
	v_mul_f32_e32 v14, 0xbfb8aa3b, v14
	v_mul_f32_e32 v15, 0xbfb8aa3b, v15
	v_exp_f32_e32 v12, v12
	v_exp_f32_e32 v13, v13
	v_exp_f32_e32 v14, v14
	v_exp_f32_e32 v15, v15
	v_lshlrev_b32_e32 v158, 16, v230
	v_and_b32_e32 v230, 0xffff0000, v230
	v_pk_add_f32 v[12:13], v[12:13], 1.0 op_sel_hi:[1,0]
	v_pk_add_f32 v[14:15], v[14:15], 1.0 op_sel_hi:[1,0]
	v_lshlrev_b32_e32 v167, 16, v231
	v_and_b32_e32 v231, 0xffff0000, v231
	v_div_scale_f32 v140, s[6:7], v12, v12, v158
	v_div_scale_f32 v141, s[6:7], v13, v13, v230
	v_rcp_f32_e32 v144, v140
	v_rcp_f32_e32 v145, v141
	v_div_scale_f32 v142, vcc, v158, v12, v158
	v_div_scale_f32 v143, s[6:7], v230, v13, v230
	v_fma_f32 v146, -v140, v144, 1.0
	v_fma_f32 v147, -v141, v145, 1.0
	v_fmac_f32_e32 v144, v146, v144
	v_fmac_f32_e32 v145, v147, v145
	v_mul_f32_e32 v148, v142, v144
	v_mul_f32_e32 v149, v143, v145
	v_fma_f32 v146, -v140, v148, v142
	v_fma_f32 v147, -v141, v149, v143
	v_fmac_f32_e32 v148, v146, v144
	v_fmac_f32_e32 v149, v147, v145
	v_fma_f32 v146, -v140, v148, v142
	v_fma_f32 v147, -v141, v149, v143
	v_div_fmas_f32 v146, v146, v144, v148
	s_mov_b64 vcc, s[6:7]
	v_div_fixup_f32 v12, v146, v12, v158
	s_nop 1
	v_div_fmas_f32 v147, v147, v145, v149
	v_div_fixup_f32 v13, v147, v13, v230
	v_div_scale_f32 v140, s[6:7], v14, v14, v167
	v_div_scale_f32 v141, s[6:7], v15, v15, v231
	v_rcp_f32_e32 v144, v140
	v_rcp_f32_e32 v145, v141
	v_div_scale_f32 v142, vcc, v167, v14, v167
	v_div_scale_f32 v143, s[6:7], v231, v15, v231
	v_fma_f32 v146, -v140, v144, 1.0
	v_fma_f32 v147, -v141, v145, 1.0
	v_fmac_f32_e32 v144, v146, v144
	v_fmac_f32_e32 v145, v147, v145
	v_mul_f32_e32 v148, v142, v144
	v_mul_f32_e32 v149, v143, v145
	v_fma_f32 v146, -v140, v148, v142
	v_fma_f32 v147, -v141, v149, v143
	v_fmac_f32_e32 v148, v146, v144
	v_fmac_f32_e32 v149, v147, v145
	v_fma_f32 v146, -v140, v148, v142
	v_fma_f32 v147, -v141, v149, v143
	v_div_fmas_f32 v146, v146, v144, v148
	s_mov_b64 vcc, s[6:7]
	v_div_fixup_f32 v14, v146, v14, v167
	s_nop 1
	v_div_fmas_f32 v147, v147, v145, v149
	v_div_fixup_f32 v15, v147, v15, v231
	v_cvt_pk_bf16_f32 v12, v12, v13
	v_cvt_pk_bf16_f32 v13, v14, v15
	s_waitcnt vmcnt(8)
	v_mul_f32_e32 v8, 0xbfb8aa3b, v8
	v_mul_f32_e32 v9, 0xbfb8aa3b, v9
	v_mul_f32_e32 v10, 0xbfb8aa3b, v10
	v_mul_f32_e32 v11, 0xbfb8aa3b, v11
	v_exp_f32_e32 v8, v8
	v_exp_f32_e32 v9, v9
	v_exp_f32_e32 v10, v10
	v_exp_f32_e32 v11, v11
	v_lshlrev_b32_e32 v158, 16, v232
	v_and_b32_e32 v232, 0xffff0000, v232
	v_pk_add_f32 v[8:9], v[8:9], 1.0 op_sel_hi:[1,0]
	v_pk_add_f32 v[10:11], v[10:11], 1.0 op_sel_hi:[1,0]
	v_lshlrev_b32_e32 v167, 16, v233
	v_and_b32_e32 v233, 0xffff0000, v233
	v_div_scale_f32 v140, s[6:7], v8, v8, v158
	v_div_scale_f32 v141, s[6:7], v9, v9, v232
	v_rcp_f32_e32 v144, v140
	v_rcp_f32_e32 v145, v141
	v_div_scale_f32 v142, vcc, v158, v8, v158
	v_div_scale_f32 v143, s[6:7], v232, v9, v232
	v_fma_f32 v146, -v140, v144, 1.0
	v_fma_f32 v147, -v141, v145, 1.0
	v_fmac_f32_e32 v144, v146, v144
	v_fmac_f32_e32 v145, v147, v145
	v_mul_f32_e32 v148, v142, v144
	v_mul_f32_e32 v149, v143, v145
	v_fma_f32 v146, -v140, v148, v142
	v_fma_f32 v147, -v141, v149, v143
	v_fmac_f32_e32 v148, v146, v144
	v_fmac_f32_e32 v149, v147, v145
	v_fma_f32 v146, -v140, v148, v142
	v_fma_f32 v147, -v141, v149, v143
	v_div_fmas_f32 v146, v146, v144, v148
	s_mov_b64 vcc, s[6:7]
	v_div_fixup_f32 v8, v146, v8, v158
	s_nop 1
	v_div_fmas_f32 v147, v147, v145, v149
	v_div_fixup_f32 v9, v147, v9, v232
	v_div_scale_f32 v140, s[6:7], v10, v10, v167
	v_div_scale_f32 v141, s[6:7], v11, v11, v233
	v_rcp_f32_e32 v144, v140
	v_rcp_f32_e32 v145, v141
	v_div_scale_f32 v142, vcc, v167, v10, v167
	v_div_scale_f32 v143, s[6:7], v233, v11, v233
	v_fma_f32 v146, -v140, v144, 1.0
	v_fma_f32 v147, -v141, v145, 1.0
	v_fmac_f32_e32 v144, v146, v144
	v_fmac_f32_e32 v145, v147, v145
	v_mul_f32_e32 v148, v142, v144
	v_mul_f32_e32 v149, v143, v145
	v_fma_f32 v146, -v140, v148, v142
	v_fma_f32 v147, -v141, v149, v143
	v_fmac_f32_e32 v148, v146, v144
	v_fmac_f32_e32 v149, v147, v145
	v_fma_f32 v146, -v140, v148, v142
	v_fma_f32 v147, -v141, v149, v143
	v_div_fmas_f32 v146, v146, v144, v148
	s_mov_b64 vcc, s[6:7]
	v_div_fixup_f32 v10, v146, v10, v167
	s_nop 1
	v_div_fmas_f32 v147, v147, v145, v149
	v_div_fixup_f32 v11, v147, v11, v233
	v_cvt_pk_bf16_f32 v8, v8, v9
	v_cvt_pk_bf16_f32 v9, v10, v11
	v_cndmask_b32_e64 v14, v12, v8, s[8:9]
	v_cndmask_b32_e64 v15, v13, v9, s[8:9]
	v_cndmask_b32_e64 v10, v8, v12, s[8:9]
	v_cndmask_b32_e64 v11, v9, v13, s[8:9]
	ds_permute_b32 v12, v159, v14
	ds_permute_b32 v13, v159, v15
	ds_permute_b32 v8, v166, v10
	ds_permute_b32 v9, v166, v11
	s_waitcnt lgkmcnt(4)
	v_cndmask_b32_e64 v46, v40, v44, s[10:11]
	v_cndmask_b32_e64 v47, v41, v45, s[10:11]
	v_cndmask_b32_e64 v44, v44, v40, s[10:11]
	v_cndmask_b32_e64 v45, v45, v41, s[10:11]
	v_add_u32_e32 v169, 0x50000, v168
	global_store_dwordx4 v169, v[44:47], s[12:13]
	s_waitcnt vmcnt(8)
	v_mul_f32_e32 v36, 0xbfb8aa3b, v36
	v_mul_f32_e32 v37, 0xbfb8aa3b, v37
	v_mul_f32_e32 v38, 0xbfb8aa3b, v38
	v_mul_f32_e32 v39, 0xbfb8aa3b, v39
	v_exp_f32_e32 v36, v36
	v_exp_f32_e32 v37, v37
	v_exp_f32_e32 v38, v38
	v_exp_f32_e32 v39, v39
	v_lshlrev_b32_e32 v158, 16, v150
	v_and_b32_e32 v150, 0xffff0000, v150
	v_pk_add_f32 v[36:37], v[36:37], 1.0 op_sel_hi:[1,0]
	v_pk_add_f32 v[38:39], v[38:39], 1.0 op_sel_hi:[1,0]
	v_lshlrev_b32_e32 v167, 16, v151
	v_and_b32_e32 v151, 0xffff0000, v151
	v_div_scale_f32 v140, s[6:7], v36, v36, v158
	v_div_scale_f32 v141, s[6:7], v37, v37, v150
	v_rcp_f32_e32 v144, v140
	v_rcp_f32_e32 v145, v141
	v_div_scale_f32 v142, vcc, v158, v36, v158
	v_div_scale_f32 v143, s[6:7], v150, v37, v150
	v_fma_f32 v146, -v140, v144, 1.0
	v_fma_f32 v147, -v141, v145, 1.0
	v_fmac_f32_e32 v144, v146, v144
	v_fmac_f32_e32 v145, v147, v145
	v_mul_f32_e32 v148, v142, v144
	v_mul_f32_e32 v149, v143, v145
	v_fma_f32 v146, -v140, v148, v142
	v_fma_f32 v147, -v141, v149, v143
	v_fmac_f32_e32 v148, v146, v144
	v_fmac_f32_e32 v149, v147, v145
	v_fma_f32 v146, -v140, v148, v142
	v_fma_f32 v147, -v141, v149, v143
	v_div_fmas_f32 v146, v146, v144, v148
	s_mov_b64 vcc, s[6:7]
	v_div_fixup_f32 v36, v146, v36, v158
	s_nop 1
	v_div_fmas_f32 v147, v147, v145, v149
	v_div_fixup_f32 v37, v147, v37, v150
	v_div_scale_f32 v140, s[6:7], v38, v38, v167
	v_div_scale_f32 v141, s[6:7], v39, v39, v151
	v_rcp_f32_e32 v144, v140
	v_rcp_f32_e32 v145, v141
	v_div_scale_f32 v142, vcc, v167, v38, v167
	v_div_scale_f32 v143, s[6:7], v151, v39, v151
	v_fma_f32 v146, -v140, v144, 1.0
	v_fma_f32 v147, -v141, v145, 1.0
	v_fmac_f32_e32 v144, v146, v144
	v_fmac_f32_e32 v145, v147, v145
	v_mul_f32_e32 v148, v142, v144
	v_mul_f32_e32 v149, v143, v145
	v_fma_f32 v146, -v140, v148, v142
	v_fma_f32 v147, -v141, v149, v143
	v_fmac_f32_e32 v148, v146, v144
	v_fmac_f32_e32 v149, v147, v145
	v_fma_f32 v146, -v140, v148, v142
	v_fma_f32 v147, -v141, v149, v143
	v_div_fmas_f32 v146, v146, v144, v148
	s_mov_b64 vcc, s[6:7]
	v_div_fixup_f32 v38, v146, v38, v167
	s_nop 1
	v_div_fmas_f32 v147, v147, v145, v149
	v_div_fixup_f32 v39, v147, v39, v151
	v_cvt_pk_bf16_f32 v36, v36, v37
	v_cvt_pk_bf16_f32 v37, v38, v39
	s_waitcnt vmcnt(7)
	v_mul_f32_e32 v32, 0xbfb8aa3b, v32
	v_mul_f32_e32 v33, 0xbfb8aa3b, v33
	v_mul_f32_e32 v34, 0xbfb8aa3b, v34
	v_mul_f32_e32 v35, 0xbfb8aa3b, v35
	v_exp_f32_e32 v32, v32
	v_exp_f32_e32 v33, v33
	v_exp_f32_e32 v34, v34
	v_exp_f32_e32 v35, v35
	v_lshlrev_b32_e32 v158, 16, v152
	v_and_b32_e32 v152, 0xffff0000, v152
	v_pk_add_f32 v[32:33], v[32:33], 1.0 op_sel_hi:[1,0]
	v_pk_add_f32 v[34:35], v[34:35], 1.0 op_sel_hi:[1,0]
	v_lshlrev_b32_e32 v167, 16, v153
	v_and_b32_e32 v153, 0xffff0000, v153
	v_div_scale_f32 v140, s[6:7], v32, v32, v158
	v_div_scale_f32 v141, s[6:7], v33, v33, v152
	v_rcp_f32_e32 v144, v140
	v_rcp_f32_e32 v145, v141
	v_div_scale_f32 v142, vcc, v158, v32, v158
	v_div_scale_f32 v143, s[6:7], v152, v33, v152
	v_fma_f32 v146, -v140, v144, 1.0
	v_fma_f32 v147, -v141, v145, 1.0
	v_fmac_f32_e32 v144, v146, v144
	v_fmac_f32_e32 v145, v147, v145
	v_mul_f32_e32 v148, v142, v144
	v_mul_f32_e32 v149, v143, v145
	v_fma_f32 v146, -v140, v148, v142
	v_fma_f32 v147, -v141, v149, v143
	v_fmac_f32_e32 v148, v146, v144
	v_fmac_f32_e32 v149, v147, v145
	v_fma_f32 v146, -v140, v148, v142
	v_fma_f32 v147, -v141, v149, v143
	v_div_fmas_f32 v146, v146, v144, v148
	s_mov_b64 vcc, s[6:7]
	v_div_fixup_f32 v32, v146, v32, v158
	s_nop 1
	v_div_fmas_f32 v147, v147, v145, v149
	v_div_fixup_f32 v33, v147, v33, v152
	v_div_scale_f32 v140, s[6:7], v34, v34, v167
	v_div_scale_f32 v141, s[6:7], v35, v35, v153
	v_rcp_f32_e32 v144, v140
	v_rcp_f32_e32 v145, v141
	v_div_scale_f32 v142, vcc, v167, v34, v167
	v_div_scale_f32 v143, s[6:7], v153, v35, v153
	v_fma_f32 v146, -v140, v144, 1.0
	v_fma_f32 v147, -v141, v145, 1.0
	v_fmac_f32_e32 v144, v146, v144
	v_fmac_f32_e32 v145, v147, v145
	v_mul_f32_e32 v148, v142, v144
	v_mul_f32_e32 v149, v143, v145
	v_fma_f32 v146, -v140, v148, v142
	v_fma_f32 v147, -v141, v149, v143
	v_fmac_f32_e32 v148, v146, v144
	v_fmac_f32_e32 v149, v147, v145
	v_fma_f32 v146, -v140, v148, v142
	v_fma_f32 v147, -v141, v149, v143
	v_div_fmas_f32 v146, v146, v144, v148
	s_mov_b64 vcc, s[6:7]
	v_div_fixup_f32 v34, v146, v34, v167
	s_nop 1
	v_div_fmas_f32 v147, v147, v145, v149
	v_div_fixup_f32 v35, v147, v35, v153
	v_cvt_pk_bf16_f32 v32, v32, v33
	v_cvt_pk_bf16_f32 v33, v34, v35
	v_cndmask_b32_e64 v38, v36, v32, s[8:9]
	v_cndmask_b32_e64 v39, v37, v33, s[8:9]
	v_cndmask_b32_e64 v34, v32, v36, s[8:9]
	v_cndmask_b32_e64 v35, v33, v37, s[8:9]
	ds_permute_b32 v36, v159, v38
	ds_permute_b32 v37, v159, v39
	ds_permute_b32 v32, v166, v34
	ds_permute_b32 v33, v166, v35
	s_waitcnt lgkmcnt(4)
	v_cndmask_b32_e64 v14, v8, v12, s[10:11]
	v_cndmask_b32_e64 v15, v9, v13, s[10:11]
	v_cndmask_b32_e64 v12, v12, v8, s[10:11]
	v_cndmask_b32_e64 v13, v13, v9, s[10:11]
	v_add_u32_e32 v169, 0x50100, v168
	global_store_dwordx4 v169, v[12:15], s[12:13]
	s_waitcnt vmcnt(7)
	v_mul_f32_e32 v4, 0xbfb8aa3b, v4
	v_mul_f32_e32 v5, 0xbfb8aa3b, v5
	v_mul_f32_e32 v6, 0xbfb8aa3b, v6
	v_mul_f32_e32 v7, 0xbfb8aa3b, v7
	v_exp_f32_e32 v4, v4
	v_exp_f32_e32 v5, v5
	v_exp_f32_e32 v6, v6
	v_exp_f32_e32 v7, v7
	v_lshlrev_b32_e32 v158, 16, v154
	v_and_b32_e32 v154, 0xffff0000, v154
	v_pk_add_f32 v[4:5], v[4:5], 1.0 op_sel_hi:[1,0]
	v_pk_add_f32 v[6:7], v[6:7], 1.0 op_sel_hi:[1,0]
	v_lshlrev_b32_e32 v167, 16, v155
	v_and_b32_e32 v155, 0xffff0000, v155
	v_div_scale_f32 v140, s[6:7], v4, v4, v158
	v_div_scale_f32 v141, s[6:7], v5, v5, v154
	v_rcp_f32_e32 v144, v140
	v_rcp_f32_e32 v145, v141
	v_div_scale_f32 v142, vcc, v158, v4, v158
	v_div_scale_f32 v143, s[6:7], v154, v5, v154
	v_fma_f32 v146, -v140, v144, 1.0
	v_fma_f32 v147, -v141, v145, 1.0
	v_fmac_f32_e32 v144, v146, v144
	v_fmac_f32_e32 v145, v147, v145
	v_mul_f32_e32 v148, v142, v144
	v_mul_f32_e32 v149, v143, v145
	v_fma_f32 v146, -v140, v148, v142
	v_fma_f32 v147, -v141, v149, v143
	v_fmac_f32_e32 v148, v146, v144
	v_fmac_f32_e32 v149, v147, v145
	v_fma_f32 v146, -v140, v148, v142
	v_fma_f32 v147, -v141, v149, v143
	v_div_fmas_f32 v146, v146, v144, v148
	s_mov_b64 vcc, s[6:7]
	v_div_fixup_f32 v4, v146, v4, v158
	s_nop 1
	v_div_fmas_f32 v147, v147, v145, v149
	v_div_fixup_f32 v5, v147, v5, v154
	v_div_scale_f32 v140, s[6:7], v6, v6, v167
	v_div_scale_f32 v141, s[6:7], v7, v7, v155
	v_rcp_f32_e32 v144, v140
	v_rcp_f32_e32 v145, v141
	v_div_scale_f32 v142, vcc, v167, v6, v167
	v_div_scale_f32 v143, s[6:7], v155, v7, v155
	v_fma_f32 v146, -v140, v144, 1.0
	v_fma_f32 v147, -v141, v145, 1.0
	v_fmac_f32_e32 v144, v146, v144
	v_fmac_f32_e32 v145, v147, v145
	v_mul_f32_e32 v148, v142, v144
	v_mul_f32_e32 v149, v143, v145
	v_fma_f32 v146, -v140, v148, v142
	v_fma_f32 v147, -v141, v149, v143
	v_fmac_f32_e32 v148, v146, v144
	v_fmac_f32_e32 v149, v147, v145
	v_fma_f32 v146, -v140, v148, v142
	v_fma_f32 v147, -v141, v149, v143
	v_div_fmas_f32 v146, v146, v144, v148
	s_mov_b64 vcc, s[6:7]
	v_div_fixup_f32 v6, v146, v6, v167
	s_nop 1
	v_div_fmas_f32 v147, v147, v145, v149
	v_div_fixup_f32 v7, v147, v7, v155
	v_cvt_pk_bf16_f32 v4, v4, v5
	v_cvt_pk_bf16_f32 v5, v6, v7
	s_waitcnt vmcnt(6)
	v_mul_f32_e32 v0, 0xbfb8aa3b, v0
	v_mul_f32_e32 v1, 0xbfb8aa3b, v1
	v_mul_f32_e32 v2, 0xbfb8aa3b, v2
	v_mul_f32_e32 v3, 0xbfb8aa3b, v3
	v_exp_f32_e32 v0, v0
	v_exp_f32_e32 v1, v1
	v_exp_f32_e32 v2, v2
	v_exp_f32_e32 v3, v3
	v_lshlrev_b32_e32 v158, 16, v156
	v_and_b32_e32 v156, 0xffff0000, v156
	v_pk_add_f32 v[0:1], v[0:1], 1.0 op_sel_hi:[1,0]
	v_pk_add_f32 v[2:3], v[2:3], 1.0 op_sel_hi:[1,0]
	v_lshlrev_b32_e32 v167, 16, v157
	v_and_b32_e32 v157, 0xffff0000, v157
	v_div_scale_f32 v140, s[6:7], v0, v0, v158
	v_div_scale_f32 v141, s[6:7], v1, v1, v156
	v_rcp_f32_e32 v144, v140
	v_rcp_f32_e32 v145, v141
	v_div_scale_f32 v142, vcc, v158, v0, v158
	v_div_scale_f32 v143, s[6:7], v156, v1, v156
	v_fma_f32 v146, -v140, v144, 1.0
	v_fma_f32 v147, -v141, v145, 1.0
	v_fmac_f32_e32 v144, v146, v144
	v_fmac_f32_e32 v145, v147, v145
	v_mul_f32_e32 v148, v142, v144
	v_mul_f32_e32 v149, v143, v145
	v_fma_f32 v146, -v140, v148, v142
	v_fma_f32 v147, -v141, v149, v143
	v_fmac_f32_e32 v148, v146, v144
	v_fmac_f32_e32 v149, v147, v145
	v_fma_f32 v146, -v140, v148, v142
	v_fma_f32 v147, -v141, v149, v143
	v_div_fmas_f32 v146, v146, v144, v148
	s_mov_b64 vcc, s[6:7]
	v_div_fixup_f32 v0, v146, v0, v158
	s_nop 1
	v_div_fmas_f32 v147, v147, v145, v149
	v_div_fixup_f32 v1, v147, v1, v156
	v_div_scale_f32 v140, s[6:7], v2, v2, v167
	v_div_scale_f32 v141, s[6:7], v3, v3, v157
	v_rcp_f32_e32 v144, v140
	v_rcp_f32_e32 v145, v141
	v_div_scale_f32 v142, vcc, v167, v2, v167
	v_div_scale_f32 v143, s[6:7], v157, v3, v157
	v_fma_f32 v146, -v140, v144, 1.0
	v_fma_f32 v147, -v141, v145, 1.0
	v_fmac_f32_e32 v144, v146, v144
	v_fmac_f32_e32 v145, v147, v145
	v_mul_f32_e32 v148, v142, v144
	v_mul_f32_e32 v149, v143, v145
	v_fma_f32 v146, -v140, v148, v142
	v_fma_f32 v147, -v141, v149, v143
	v_fmac_f32_e32 v148, v146, v144
	v_fmac_f32_e32 v149, v147, v145
	v_fma_f32 v146, -v140, v148, v142
	v_fma_f32 v147, -v141, v149, v143
	v_div_fmas_f32 v146, v146, v144, v148
	s_mov_b64 vcc, s[6:7]
	v_div_fixup_f32 v2, v146, v2, v167
	s_nop 1
	v_div_fmas_f32 v147, v147, v145, v149
	v_div_fixup_f32 v3, v147, v3, v157
	v_cvt_pk_bf16_f32 v0, v0, v1
	v_cvt_pk_bf16_f32 v1, v2, v3
	v_cndmask_b32_e64 v6, v4, v0, s[8:9]
	v_cndmask_b32_e64 v7, v5, v1, s[8:9]
	v_cndmask_b32_e64 v2, v0, v4, s[8:9]
	v_cndmask_b32_e64 v3, v1, v5, s[8:9]
	ds_permute_b32 v4, v159, v6
	ds_permute_b32 v5, v159, v7
	ds_permute_b32 v0, v166, v2
	ds_permute_b32 v1, v166, v3
	s_waitcnt lgkmcnt(4)
	v_cndmask_b32_e64 v38, v32, v36, s[10:11]
	v_cndmask_b32_e64 v39, v33, v37, s[10:11]
	v_cndmask_b32_e64 v36, v36, v32, s[10:11]
	v_cndmask_b32_e64 v37, v37, v33, s[10:11]
	v_add_u32_e32 v169, 0x58000, v168
	global_store_dwordx4 v169, v[36:39], s[12:13]
	s_waitcnt lgkmcnt(0)
	v_cndmask_b32_e64 v6, v0, v4, s[10:11]
	v_cndmask_b32_e64 v7, v1, v5, s[10:11]
	v_cndmask_b32_e64 v4, v4, v0, s[10:11]
	v_cndmask_b32_e64 v5, v5, v1, s[10:11]
	v_add_u32_e32 v169, 0x58100, v168
	global_store_dwordx4 v169, v[4:7], s[12:13]
.Lglu_end:
	s_mov_b64 s[8:9], s[26:27]
	s_mov_b64 s[10:11], s[24:25]
	s_mov_b32 s7, s20
	s_mov_b32 s6, s22
	s_and_b64 vcc, exec, s[4:5]
	s_cbranch_vccz .LBB0_1174
	s_waitcnt vmcnt(0)
	s_cmpk_gt_u32 s30, 0xff
	s_cbranch_scc1 .LBB0_1181
	s_barrier
